# sample-batch ring prefetch + prompt scoring ring, fix-up units whole (not split), stagger+deep dense attention
# speedup vs baseline: 1.0138x; 1.0027x over previous
; #define PG8_LAS __attribute__((address_space(3)))
; __device__ __forceinline__ int fresh_tid() { int t = threadIdx.x; asm volatile("" : "+v"(t)); return t; }
;     const int tid_ = fresh_tid(), lane = tid_ & 63, wave = __builtin_amdgcn_readfirstlane(tid_ >> 6), r = lane & 31, kh = lane >> 5;
;     unsigned char* ws = p.ws;
;     const bf16_t* QI = (const bf16_t*)(ws + WS_QI); const float* WI = (const float*)(ws + WS_WI); unsigned long long* BM = (unsigned long long*)(ws + WS_BM);
;     const bf16_t* KIH = (const bf16_t*)(ws + WS_KIH); const bf16_t* KIL = (const bf16_t*)(ws + WS_KIL);
;     PG8_LAS float* sc = (PG8_LAS float*)lds;
;     const int b = s & 1, q0 = (s >> 1) * 8, grow0 = b * SEQ + q0, ntile = (q0 + 8 + 31) >> 5;
;     IdxQ qa, qb; idx_load_q(qa, QI, WI, grow0, lane); idx_load_q(qb, QI, WI, grow0 + 4, lane);
;     const size_t kbase = (size_t)(b * SEQ + r) * IDD + kh * 8;
;     IdxKey kn;
;     if (wave < ntile) idx_load_keyb(kn, KIH + kbase + (size_t)wave * 32 * IDD, KIL + kbase + (size_t)wave * 32 * IDD);
;     for (int t = wave; t < ntile; t += NWAVES) {
;         const IdxKey k = kn;
;         if (t + NWAVES < ntile) idx_load_keyb(kn, KIH + kbase + (size_t)(t + NWAVES) * 32 * IDD, KIL + kbase + (size_t)(t + NWAVES) * 32 * IDD);
;         float sa[2], sb[2]; idx_tile(qa, k, sa); idx_tile(qb, k, sb);
;         const int col = t * 32 + r;
;         sc[(2 * kh) * SCP_LD + col] = sa[0]; sc[(2 * kh + 1) * SCP_LD + col] = sa[1];
;         sc[(4 + 2 * kh) * SCP_LD + col] = sb[0]; sc[(5 + 2 * kh) * SCP_LD + col] = sb[1];
;     }
; __device__ __forceinline__ void mid1_phase(const Params& p, PG8_LAS unsigned char* lds) {
;     ...
;     for (;;) {
;         const unsigned idx = wq_next(ctr, lds);
;         if (idx >= NA + NC_ + NB2) break;
;         if (idx < NA) idx_sample_batch_unit(p, lds, (int)idx);
;         else if (idx < NA + NC_) { const unsigned g = idx - NA; lru_local_unit(p, lds, (int)(g & 7u), (LRU_NGRP - 1 - (int)(g >> 3)) * LRU_GRP); }
;         else { const int s2 = (int)(NB_ - 1 - 2 * (idx - NA - NC_)); idx_prompt_unit(p, lds, s2); __syncthreads(); idx_prompt_unit(p, lds, s2 - 1); }
.LBB0_871:
	s_or_b64 exec, exec, s[0:1]
	s_waitcnt lgkmcnt(0)
	s_barrier
	ds_read_b32 v2, v156
	s_movk_i32 s0, 0x327
	s_waitcnt lgkmcnt(0)
	v_cmp_lt_u32_e32 vcc, s0, v2
	v_readfirstlane_b32 s40, v2
	s_mov_b64 s[0:1], -1
	s_cbranch_vccnz .LBB0_866
	s_cmp_gt_u32 s40, 31
	s_cbranch_scc0 .LBB0_1691
	s_cmpk_gt_u32 s40, 0x127
	s_cbranch_scc0 .LBB0_1553
	v_mov_b32_e32 v2, v0
	s_nop 0
	v_readfirstlane_b32 s0, v2
	s_ashr_i32 s4, s0, 6
	s_lshl_b32 s0, s40, 3
	s_sub_i32 s0, 0x938, s0
	s_and_b32 s10, s0, 0xff8
	s_add_i32 s0, s10, 39
	s_or_b32 s12, s10, 0x1000
	s_lshr_b32 s11, s0, 5
	s_cmp_ge_i32 s4, s11
	v_and_b32_e32 v84, 63, v2
	s_cbranch_scc1 .LBB0_879
	v_and_b32_e32 v3, 31, v2
	v_lshrrev_b32_e32 v5, 5, v84
	v_lshrrev_b32_e32 v4, 1, v84
	v_and_b32_e32 v6, 2, v4
	v_bfe_u32 v7, v2, 4, 1
	v_and_b32_e32 v8, 3, v2
	v_and_or_b32 v8, v4, 4, v8
	v_or3_b32 v9, s12, v7, v6
	v_lshlrev_b32_e32 v10, 10, v9
	v_lshl_add_u32 v10, v8, 7, v10
	v_lshl_add_u32 v10, v5, 4, v10
	v_add_u32_e32 v11, 0x1000, v10
	s_lshl_b32 s1, s12, 5
	v_lshl_add_u32 v12, v5, 6, s1
	global_load_dwordx4 v[18:21], v10, s[64:65]
	global_load_dwordx4 v[22:25], v10, s[64:65] offset:32
	global_load_dwordx4 v[26:29], v10, s[64:65] offset:64
	global_load_dwordx4 v[30:33], v10, s[64:65] offset:96
	global_load_dwordx4 v[34:37], v11, s[64:65]
	global_load_dwordx4 v[38:41], v11, s[64:65] offset:32
	global_load_dwordx4 v[42:45], v11, s[64:65] offset:64
	global_load_dwordx4 v[46:49], v11, s[64:65] offset:96
	global_load_dwordx4 v[50:53], v12, s[66:67]
	global_load_dwordx4 v[54:57], v12, s[66:67] offset:16
	global_load_dwordx4 v[58:61], v12, s[66:67] offset:32
	global_load_dwordx4 v[62:65], v12, s[66:67] offset:48
	global_load_dwordx4 v[66:69], v12, s[66:67] offset:128
	global_load_dwordx4 v[70:73], v12, s[66:67] offset:144
	global_load_dwordx4 v[74:77], v12, s[66:67] offset:160
	global_load_dwordx4 v[78:81], v12, s[66:67] offset:176
	s_add_u32 s6, s34, 0x22f02000
	s_addc_u32 s7, s35, 0
	s_lshl_b32 s1, s4, 12
	v_lshl_add_u32 v94, v3, 7, s1
	v_lshl_add_u32 v94, v5, 4, v94
	s_sub_i32 s3, s11, s4
	s_add_i32 s3, s3, 7
	s_lshr_b32 s3, s3, 3
	global_load_dwordx4 v[102:105], v94, s[6:7]
	global_load_dwordx4 v[106:109], v94, s[6:7] offset:32
	global_load_dwordx4 v[110:113], v94, s[6:7] offset:64
	global_load_dwordx4 v[114:117], v94, s[6:7] offset:96
	s_cmp_lt_u32 s3, 2
	s_cbranch_scc1 .LidxA_pd
	v_add_u32_e32 v95, 0x8000, v94
	global_load_dwordx4 v[118:121], v95, s[6:7]
	global_load_dwordx4 v[122:125], v95, s[6:7] offset:32
	global_load_dwordx4 v[126:129], v95, s[6:7] offset:64
	global_load_dwordx4 v[130:133], v95, s[6:7] offset:96
	s_cmp_lt_u32 s3, 3
	s_cbranch_scc1 .LidxA_pd
	v_add_u32_e32 v95, 0x10000, v94
	global_load_dwordx4 v[134:137], v95, s[6:7]
	global_load_dwordx4 v[138:141], v95, s[6:7] offset:32
	global_load_dwordx4 v[142:145], v95, s[6:7] offset:64
	global_load_dwordx4 v[146:149], v95, s[6:7] offset:96
	s_cmp_lt_u32 s3, 4
	s_cbranch_scc1 .LidxA_pd
	v_add_u32_e32 v95, 0x18000, v94
	global_load_dwordx4 v[160:163], v95, s[6:7]
	global_load_dwordx4 v[164:167], v95, s[6:7] offset:32
	global_load_dwordx4 v[168:171], v95, s[6:7] offset:64
	global_load_dwordx4 v[172:175], v95, s[6:7] offset:96
.LidxA_pd:
	v_add_u32_e32 v95, 0x20000, v94
	s_lshl_b32 s1, s4, 7
	v_lshl_add_u32 v92, v5, 15, s1
	v_lshl_add_u32 v92, v3, 2, v92
	v_add_u32_e32 v92, 0x10000, v92
	s_mov_b32 s5, 0
	s_sub_i32 s1, s3, s5
	s_cmp_gt_i32 s1, 3
	s_cbranch_scc1 .LidxA_w12_p
	s_cmp_eq_u32 s1, 3
	s_cbranch_scc1 .LidxA_w8_p
	s_cmp_eq_u32 s1, 2
	s_cbranch_scc1 .LidxA_w4_p
	s_waitcnt vmcnt(0)
	s_branch .LidxA_gp
.LidxA_w4_p:
	s_waitcnt vmcnt(4)
	s_branch .LidxA_gp
.LidxA_w8_p:
	s_waitcnt vmcnt(8)
	s_branch .LidxA_gp
.LidxA_w12_p:
	s_waitcnt vmcnt(12)
.LidxA_gp:
	v_mul_f32_e32 v50, 0x3eb504f3, v50
	v_mul_f32_e32 v51, 0x3eb504f3, v51
	v_mul_f32_e32 v52, 0x3eb504f3, v52
	v_mul_f32_e32 v53, 0x3eb504f3, v53
	v_mul_f32_e32 v54, 0x3eb504f3, v54
	v_mul_f32_e32 v55, 0x3eb504f3, v55
	v_mul_f32_e32 v56, 0x3eb504f3, v56
	v_mul_f32_e32 v57, 0x3eb504f3, v57
	v_mul_f32_e32 v58, 0x3eb504f3, v58
	v_mul_f32_e32 v59, 0x3eb504f3, v59
	v_mul_f32_e32 v60, 0x3eb504f3, v60
	v_mul_f32_e32 v61, 0x3eb504f3, v61
	v_mul_f32_e32 v62, 0x3eb504f3, v62
	v_mul_f32_e32 v63, 0x3eb504f3, v63
	v_mul_f32_e32 v64, 0x3eb504f3, v64
	v_mul_f32_e32 v65, 0x3eb504f3, v65
	v_mul_f32_e32 v66, 0x3eb504f3, v66
	v_mul_f32_e32 v67, 0x3eb504f3, v67
	v_mul_f32_e32 v68, 0x3eb504f3, v68
	v_mul_f32_e32 v69, 0x3eb504f3, v69
	v_mul_f32_e32 v70, 0x3eb504f3, v70
	v_mul_f32_e32 v71, 0x3eb504f3, v71
	v_mul_f32_e32 v72, 0x3eb504f3, v72
	v_mul_f32_e32 v73, 0x3eb504f3, v73
	v_mul_f32_e32 v74, 0x3eb504f3, v74
	v_mul_f32_e32 v75, 0x3eb504f3, v75
	v_mul_f32_e32 v76, 0x3eb504f3, v76
	v_mul_f32_e32 v77, 0x3eb504f3, v77
	v_mul_f32_e32 v78, 0x3eb504f3, v78
	v_mul_f32_e32 v79, 0x3eb504f3, v79
	v_mul_f32_e32 v80, 0x3eb504f3, v80
	v_mul_f32_e32 v81, 0x3eb504f3, v81
	s_branch .LidxA_go_0
.LidxA_slot_0:
	s_sub_i32 s1, s3, s5
	s_cmp_gt_i32 s1, 3
	s_cbranch_scc1 .LidxA_w12_0
	s_cmp_eq_u32 s1, 3
	s_cbranch_scc1 .LidxA_w8_0
	s_cmp_eq_u32 s1, 2
	s_cbranch_scc1 .LidxA_w4_0
	s_waitcnt vmcnt(0)
	s_branch .LidxA_go_0

; __device__ __forceinline__ void idx_tile(const IdxQ& q, const IdxKey& k, float (&s)[2]) {
;     f32x16 acc;
; #pragma unroll
;     for (int i = 0; i < 16; ++i) acc[i] = 0.f;
; #pragma unroll
;     for (int ks = 0; ks < 4; ++ks) {
;         acc = __builtin_amdgcn_mfma_f32_32x32x16_bf16(q.hi[ks], k.hi[ks], acc, 0, 0, 0);
;         if (IDX_SPLIT == 3) { acc = __builtin_amdgcn_mfma_f32_32x32x16_bf16(q.hi[ks], k.lo[ks], acc, 0, 0, 0); acc = __builtin_amdgcn_mfma_f32_32x32x16_bf16(q.lo[ks], k.hi[ks], acc, 0, 0, 0); }
;     }
; #pragma unroll
;     for (int e = 0; e < 2; ++e) {
;         float t = 0.f;
; #pragma unroll
;         for (int i = 0; i < 8; ++i) t += fmaxf(acc[e * 8 + i] * IDX_SCALE, 0.f) * q.w[e * 8 + i];
;         s[e] = t;
;     }
; }
;     ...
;     for (int t = wave; t < ntile; t += NWAVES) {
;         const IdxKey k = kn;
;         if (t + NWAVES < ntile) idx_load_keyb(kn, KIH + kbase + (size_t)(t + NWAVES) * 32 * IDD, KIL + kbase + (size_t)(t + NWAVES) * 32 * IDD);
;         float sa[2], sb[2]; idx_tile(qa, k, sa); idx_tile(qb, k, sb);
;         const int col = t * 32 + r;
;         sc[(2 * kh) * SCP_LD + col] = sa[0]; sc[(2 * kh + 1) * SCP_LD + col] = sa[1];
;         sc[(4 + 2 * kh) * SCP_LD + col] = sb[0]; sc[(5 + 2 * kh) * SCP_LD + col] = sb[1];
;     }
.LidxA_go_0:
	v_mfma_f32_32x32x16_bf16 v[2:17], v[18:21], v[102:105], 0
	v_mfma_f32_32x32x16_bf16 v[2:17], v[22:25], v[106:109], v[2:17]
	v_mfma_f32_32x32x16_bf16 v[2:17], v[26:29], v[110:113], v[2:17]
	v_mfma_f32_32x32x16_bf16 v[2:17], v[30:33], v[114:117], v[2:17]
	s_nop 11
	v_mul_f32_e32 v82, 0x3e000000, v2
	v_max_f32_e32 v82, 0, v82
	v_fma_f32 v86, v50, v82, 0
	v_mul_f32_e32 v83, 0x3e000000, v3
	v_max_f32_e32 v83, 0, v83
	v_fmac_f32_e32 v86, v51, v83
	v_mul_f32_e32 v82, 0x3e000000, v4
	v_max_f32_e32 v82, 0, v82
	v_fmac_f32_e32 v86, v52, v82
	v_mul_f32_e32 v83, 0x3e000000, v5
	v_max_f32_e32 v83, 0, v83
	v_fmac_f32_e32 v86, v53, v83
	v_mul_f32_e32 v82, 0x3e000000, v6
	v_max_f32_e32 v82, 0, v82
	v_fmac_f32_e32 v86, v54, v82
	v_mul_f32_e32 v83, 0x3e000000, v7
	v_max_f32_e32 v83, 0, v83
	v_fmac_f32_e32 v86, v55, v83
	v_mul_f32_e32 v82, 0x3e000000, v8
	v_max_f32_e32 v82, 0, v82
	v_fmac_f32_e32 v86, v56, v82
	v_mul_f32_e32 v83, 0x3e000000, v9
	v_max_f32_e32 v83, 0, v83
	v_fmac_f32_e32 v86, v57, v83
	v_mul_f32_e32 v82, 0x3e000000, v10
	v_max_f32_e32 v82, 0, v82
	v_fma_f32 v87, v58, v82, 0
	v_mul_f32_e32 v83, 0x3e000000, v11
	v_max_f32_e32 v83, 0, v83
	v_fmac_f32_e32 v87, v59, v83
	v_mul_f32_e32 v82, 0x3e000000, v12
	v_max_f32_e32 v82, 0, v82
	v_fmac_f32_e32 v87, v60, v82
	v_mul_f32_e32 v83, 0x3e000000, v13
	v_max_f32_e32 v83, 0, v83
	v_fmac_f32_e32 v87, v61, v83
	v_mul_f32_e32 v82, 0x3e000000, v14
	v_max_f32_e32 v82, 0, v82
	v_fmac_f32_e32 v87, v62, v82
	v_mul_f32_e32 v83, 0x3e000000, v15
	v_max_f32_e32 v83, 0, v83
	v_fmac_f32_e32 v87, v63, v83
	v_mul_f32_e32 v82, 0x3e000000, v16
	v_max_f32_e32 v82, 0, v82
	v_fmac_f32_e32 v87, v64, v82
	v_mul_f32_e32 v83, 0x3e000000, v17
	v_max_f32_e32 v83, 0, v83
	v_fmac_f32_e32 v87, v65, v83
	v_mfma_f32_32x32x16_bf16 v[2:17], v[34:37], v[102:105], 0
	v_mfma_f32_32x32x16_bf16 v[2:17], v[38:41], v[106:109], v[2:17]
	v_mfma_f32_32x32x16_bf16 v[2:17], v[42:45], v[110:113], v[2:17]
	v_mfma_f32_32x32x16_bf16 v[2:17], v[46:49], v[114:117], v[2:17]
	s_add_i32 s1, s5, 4
	s_cmp_lt_u32 s1, s3
	s_cbranch_scc0 .LidxA_nr_0
	global_load_dwordx4 v[102:105], v95, s[6:7]
	global_load_dwordx4 v[106:109], v95, s[6:7] offset:32
	global_load_dwordx4 v[110:113], v95, s[6:7] offset:64
	global_load_dwordx4 v[114:117], v95, s[6:7] offset:96
	v_add_u32_e32 v95, 0x8000, v95
.LidxA_nr_0:
	s_nop 8
	v_mul_f32_e32 v82, 0x3e000000, v2
	v_max_f32_e32 v82, 0, v82
	v_fma_f32 v88, v66, v82, 0
	v_mul_f32_e32 v83, 0x3e000000, v3
	v_max_f32_e32 v83, 0, v83
	v_fmac_f32_e32 v88, v67, v83
	v_mul_f32_e32 v82, 0x3e000000, v4
	v_max_f32_e32 v82, 0, v82
	v_fmac_f32_e32 v88, v68, v82
	v_mul_f32_e32 v83, 0x3e000000, v5
	v_max_f32_e32 v83, 0, v83
	v_fmac_f32_e32 v88, v69, v83
	v_mul_f32_e32 v82, 0x3e000000, v6
	v_max_f32_e32 v82, 0, v82
	v_fmac_f32_e32 v88, v70, v82
	v_mul_f32_e32 v83, 0x3e000000, v7
	v_max_f32_e32 v83, 0, v83
	v_fmac_f32_e32 v88, v71, v83
	v_mul_f32_e32 v82, 0x3e000000, v8
	v_max_f32_e32 v82, 0, v82
	v_fmac_f32_e32 v88, v72, v82
	v_mul_f32_e32 v83, 0x3e000000, v9
	v_max_f32_e32 v83, 0, v83
	v_fmac_f32_e32 v88, v73, v83
	v_mul_f32_e32 v82, 0x3e000000, v10
	v_max_f32_e32 v82, 0, v82
	v_fma_f32 v89, v74, v82, 0
	v_mul_f32_e32 v83, 0x3e000000, v11
	v_max_f32_e32 v83, 0, v83
	v_fmac_f32_e32 v89, v75, v83
	v_mul_f32_e32 v82, 0x3e000000, v12
	v_max_f32_e32 v82, 0, v82
	v_fmac_f32_e32 v89, v76, v82
	v_mul_f32_e32 v83, 0x3e000000, v13
	v_max_f32_e32 v83, 0, v83
	v_fmac_f32_e32 v89, v77, v83
	v_mul_f32_e32 v82, 0x3e000000, v14
	v_max_f32_e32 v82, 0, v82
	v_fmac_f32_e32 v89, v78, v82
	v_mul_f32_e32 v83, 0x3e000000, v15
	v_max_f32_e32 v83, 0, v83
	v_fmac_f32_e32 v89, v79, v83
	v_mul_f32_e32 v82, 0x3e000000, v16
	v_max_f32_e32 v82, 0, v82
	v_fmac_f32_e32 v89, v80, v82
	v_mul_f32_e32 v83, 0x3e000000, v17
	v_max_f32_e32 v83, 0, v83
	v_fmac_f32_e32 v89, v81, v83
	v_add_u32_e32 v93, 0xffff0000, v92
	ds_write_b32 v93, v86
	v_add_u32_e32 v93, 0xffff4000, v92
	ds_write_b32 v93, v87
	ds_write2st64_b32 v92, v88, v89 offset1:64
	v_add_u32_e32 v92, 0x400, v92
	s_add_i32 s5, s5, 1
	s_cmp_lt_u32 s5, s3
	s_cbranch_scc0 .LidxA_done

; __device__ __forceinline__ void idx_tile(const IdxQ& q, const IdxKey& k, float (&s)[2]) {
;     f32x16 acc;
; #pragma unroll
;     for (int i = 0; i < 16; ++i) acc[i] = 0.f;
; #pragma unroll
;     for (int ks = 0; ks < 4; ++ks) {
;         acc = __builtin_amdgcn_mfma_f32_32x32x16_bf16(q.hi[ks], k.hi[ks], acc, 0, 0, 0);
;         if (IDX_SPLIT == 3) { acc = __builtin_amdgcn_mfma_f32_32x32x16_bf16(q.hi[ks], k.lo[ks], acc, 0, 0, 0); acc = __builtin_amdgcn_mfma_f32_32x32x16_bf16(q.lo[ks], k.hi[ks], acc, 0, 0, 0); }
;     }
; #pragma unroll
;     for (int e = 0; e < 2; ++e) {
;         float t = 0.f;
; #pragma unroll
;         for (int i = 0; i < 8; ++i) t += fmaxf(acc[e * 8 + i] * IDX_SCALE, 0.f) * q.w[e * 8 + i];
;         s[e] = t;
;     }
; }
;     ...
;     for (int t = wave; t < ntile; t += NWAVES) {
;         const IdxKey k = kn;
;         if (t + NWAVES < ntile) idx_load_keyb(kn, KIH + kbase + (size_t)(t + NWAVES) * 32 * IDD, KIL + kbase + (size_t)(t + NWAVES) * 32 * IDD);
;         float sa[2], sb[2]; idx_tile(qa, k, sa); idx_tile(qb, k, sb);
;         const int col = t * 32 + r;
;         sc[(2 * kh) * SCP_LD + col] = sa[0]; sc[(2 * kh + 1) * SCP_LD + col] = sa[1];
;         sc[(4 + 2 * kh) * SCP_LD + col] = sb[0]; sc[(5 + 2 * kh) * SCP_LD + col] = sb[1];
;     }
.LidxA_go_1:
	v_mfma_f32_32x32x16_bf16 v[2:17], v[18:21], v[118:121], 0
	v_mfma_f32_32x32x16_bf16 v[2:17], v[22:25], v[122:125], v[2:17]
	v_mfma_f32_32x32x16_bf16 v[2:17], v[26:29], v[126:129], v[2:17]
	v_mfma_f32_32x32x16_bf16 v[2:17], v[30:33], v[130:133], v[2:17]
	s_nop 11
	v_mul_f32_e32 v82, 0x3e000000, v2
	v_max_f32_e32 v82, 0, v82
	v_fma_f32 v86, v50, v82, 0
	v_mul_f32_e32 v83, 0x3e000000, v3
	v_max_f32_e32 v83, 0, v83
	v_fmac_f32_e32 v86, v51, v83
	v_mul_f32_e32 v82, 0x3e000000, v4
	v_max_f32_e32 v82, 0, v82
	v_fmac_f32_e32 v86, v52, v82
	v_mul_f32_e32 v83, 0x3e000000, v5
	v_max_f32_e32 v83, 0, v83
	v_fmac_f32_e32 v86, v53, v83
	v_mul_f32_e32 v82, 0x3e000000, v6
	v_max_f32_e32 v82, 0, v82
	v_fmac_f32_e32 v86, v54, v82
	v_mul_f32_e32 v83, 0x3e000000, v7
	v_max_f32_e32 v83, 0, v83
	v_fmac_f32_e32 v86, v55, v83
	v_mul_f32_e32 v82, 0x3e000000, v8
	v_max_f32_e32 v82, 0, v82
	v_fmac_f32_e32 v86, v56, v82
	v_mul_f32_e32 v83, 0x3e000000, v9
	v_max_f32_e32 v83, 0, v83
	v_fmac_f32_e32 v86, v57, v83
	v_mul_f32_e32 v82, 0x3e000000, v10
	v_max_f32_e32 v82, 0, v82
	v_fma_f32 v87, v58, v82, 0
	v_mul_f32_e32 v83, 0x3e000000, v11
	v_max_f32_e32 v83, 0, v83
	v_fmac_f32_e32 v87, v59, v83
	v_mul_f32_e32 v82, 0x3e000000, v12
	v_max_f32_e32 v82, 0, v82
	v_fmac_f32_e32 v87, v60, v82
	v_mul_f32_e32 v83, 0x3e000000, v13
	v_max_f32_e32 v83, 0, v83
	v_fmac_f32_e32 v87, v61, v83
	v_mul_f32_e32 v82, 0x3e000000, v14
	v_max_f32_e32 v82, 0, v82
	v_fmac_f32_e32 v87, v62, v82
	v_mul_f32_e32 v83, 0x3e000000, v15
	v_max_f32_e32 v83, 0, v83
	v_fmac_f32_e32 v87, v63, v83
	v_mul_f32_e32 v82, 0x3e000000, v16
	v_max_f32_e32 v82, 0, v82
	v_fmac_f32_e32 v87, v64, v82
	v_mul_f32_e32 v83, 0x3e000000, v17
	v_max_f32_e32 v83, 0, v83
	v_fmac_f32_e32 v87, v65, v83
	v_mfma_f32_32x32x16_bf16 v[2:17], v[34:37], v[118:121], 0
	v_mfma_f32_32x32x16_bf16 v[2:17], v[38:41], v[122:125], v[2:17]
	v_mfma_f32_32x32x16_bf16 v[2:17], v[42:45], v[126:129], v[2:17]
	v_mfma_f32_32x32x16_bf16 v[2:17], v[46:49], v[130:133], v[2:17]
	s_add_i32 s1, s5, 4
	s_cmp_lt_u32 s1, s3
	s_cbranch_scc0 .LidxA_nr_1
	global_load_dwordx4 v[118:121], v95, s[6:7]
	global_load_dwordx4 v[122:125], v95, s[6:7] offset:32
	global_load_dwordx4 v[126:129], v95, s[6:7] offset:64
	global_load_dwordx4 v[130:133], v95, s[6:7] offset:96
	v_add_u32_e32 v95, 0x8000, v95

; __device__ __forceinline__ void idx_tile(const IdxQ& q, const IdxKey& k, float (&s)[2]) {
;     f32x16 acc;
; #pragma unroll
;     for (int i = 0; i < 16; ++i) acc[i] = 0.f;
; #pragma unroll
;     for (int ks = 0; ks < 4; ++ks) {
;         acc = __builtin_amdgcn_mfma_f32_32x32x16_bf16(q.hi[ks], k.hi[ks], acc, 0, 0, 0);
;         if (IDX_SPLIT == 3) { acc = __builtin_amdgcn_mfma_f32_32x32x16_bf16(q.hi[ks], k.lo[ks], acc, 0, 0, 0); acc = __builtin_amdgcn_mfma_f32_32x32x16_bf16(q.lo[ks], k.hi[ks], acc, 0, 0, 0); }
;     }
; #pragma unroll
;     for (int e = 0; e < 2; ++e) {
;         float t = 0.f;
; #pragma unroll
;         for (int i = 0; i < 8; ++i) t += fmaxf(acc[e * 8 + i] * IDX_SCALE, 0.f) * q.w[e * 8 + i];
;         s[e] = t;
;     }
; }
;     ...
;     for (int t = wave; t < ntile; t += NWAVES) {
;         const IdxKey k = kn;
;         if (t + NWAVES < ntile) idx_load_keyb(kn, KIH + kbase + (size_t)(t + NWAVES) * 32 * IDD, KIL + kbase + (size_t)(t + NWAVES) * 32 * IDD);
;         float sa[2], sb[2]; idx_tile(qa, k, sa); idx_tile(qb, k, sb);
;         const int col = t * 32 + r;
;         sc[(2 * kh) * SCP_LD + col] = sa[0]; sc[(2 * kh + 1) * SCP_LD + col] = sa[1];
;         sc[(4 + 2 * kh) * SCP_LD + col] = sb[0]; sc[(5 + 2 * kh) * SCP_LD + col] = sb[1];
;     }
.LidxA_go_2:
	v_mfma_f32_32x32x16_bf16 v[2:17], v[18:21], v[134:137], 0
	v_mfma_f32_32x32x16_bf16 v[2:17], v[22:25], v[138:141], v[2:17]
	v_mfma_f32_32x32x16_bf16 v[2:17], v[26:29], v[142:145], v[2:17]
	v_mfma_f32_32x32x16_bf16 v[2:17], v[30:33], v[146:149], v[2:17]
	s_nop 11
	v_mul_f32_e32 v82, 0x3e000000, v2
	v_max_f32_e32 v82, 0, v82
	v_fma_f32 v86, v50, v82, 0
	v_mul_f32_e32 v83, 0x3e000000, v3
	v_max_f32_e32 v83, 0, v83
	v_fmac_f32_e32 v86, v51, v83
	v_mul_f32_e32 v82, 0x3e000000, v4
	v_max_f32_e32 v82, 0, v82
	v_fmac_f32_e32 v86, v52, v82
	v_mul_f32_e32 v83, 0x3e000000, v5
	v_max_f32_e32 v83, 0, v83
	v_fmac_f32_e32 v86, v53, v83
	v_mul_f32_e32 v82, 0x3e000000, v6
	v_max_f32_e32 v82, 0, v82
	v_fmac_f32_e32 v86, v54, v82
	v_mul_f32_e32 v83, 0x3e000000, v7
	v_max_f32_e32 v83, 0, v83
	v_fmac_f32_e32 v86, v55, v83
	v_mul_f32_e32 v82, 0x3e000000, v8
	v_max_f32_e32 v82, 0, v82
	v_fmac_f32_e32 v86, v56, v82
	v_mul_f32_e32 v83, 0x3e000000, v9
	v_max_f32_e32 v83, 0, v83
	v_fmac_f32_e32 v86, v57, v83
	v_mul_f32_e32 v82, 0x3e000000, v10
	v_max_f32_e32 v82, 0, v82
	v_fma_f32 v87, v58, v82, 0
	v_mul_f32_e32 v83, 0x3e000000, v11
	v_max_f32_e32 v83, 0, v83
	v_fmac_f32_e32 v87, v59, v83
	v_mul_f32_e32 v82, 0x3e000000, v12
	v_max_f32_e32 v82, 0, v82
	v_fmac_f32_e32 v87, v60, v82
	v_mul_f32_e32 v83, 0x3e000000, v13
	v_max_f32_e32 v83, 0, v83
	v_fmac_f32_e32 v87, v61, v83
	v_mul_f32_e32 v82, 0x3e000000, v14
	v_max_f32_e32 v82, 0, v82
	v_fmac_f32_e32 v87, v62, v82
	v_mul_f32_e32 v83, 0x3e000000, v15
	v_max_f32_e32 v83, 0, v83
	v_fmac_f32_e32 v87, v63, v83
	v_mul_f32_e32 v82, 0x3e000000, v16
	v_max_f32_e32 v82, 0, v82
	v_fmac_f32_e32 v87, v64, v82
	v_mul_f32_e32 v83, 0x3e000000, v17
	v_max_f32_e32 v83, 0, v83
	v_fmac_f32_e32 v87, v65, v83
	v_mfma_f32_32x32x16_bf16 v[2:17], v[34:37], v[134:137], 0
	v_mfma_f32_32x32x16_bf16 v[2:17], v[38:41], v[138:141], v[2:17]
	v_mfma_f32_32x32x16_bf16 v[2:17], v[42:45], v[142:145], v[2:17]
	v_mfma_f32_32x32x16_bf16 v[2:17], v[46:49], v[146:149], v[2:17]
	s_add_i32 s1, s5, 4
	s_cmp_lt_u32 s1, s3
	s_cbranch_scc0 .LidxA_nr_2
	global_load_dwordx4 v[134:137], v95, s[6:7]
	global_load_dwordx4 v[138:141], v95, s[6:7] offset:32
	global_load_dwordx4 v[142:145], v95, s[6:7] offset:64
	global_load_dwordx4 v[146:149], v95, s[6:7] offset:96
	v_add_u32_e32 v95, 0x8000, v95

; __device__ __forceinline__ void idx_tile(const IdxQ& q, const IdxKey& k, float (&s)[2]) {
;     f32x16 acc;
; #pragma unroll
;     for (int i = 0; i < 16; ++i) acc[i] = 0.f;
; #pragma unroll
;     for (int ks = 0; ks < 4; ++ks) {
;         acc = __builtin_amdgcn_mfma_f32_32x32x16_bf16(q.hi[ks], k.hi[ks], acc, 0, 0, 0);
;         if (IDX_SPLIT == 3) { acc = __builtin_amdgcn_mfma_f32_32x32x16_bf16(q.hi[ks], k.lo[ks], acc, 0, 0, 0); acc = __builtin_amdgcn_mfma_f32_32x32x16_bf16(q.lo[ks], k.hi[ks], acc, 0, 0, 0); }
;     }
; #pragma unroll
;     for (int e = 0; e < 2; ++e) {
;         float t = 0.f;
; #pragma unroll
;         for (int i = 0; i < 8; ++i) t += fmaxf(acc[e * 8 + i] * IDX_SCALE, 0.f) * q.w[e * 8 + i];
;         s[e] = t;
;     }
; }
;     ...
;     for (int t = wave; t < ntile; t += NWAVES) {
;         const IdxKey k = kn;
;         if (t + NWAVES < ntile) idx_load_keyb(kn, KIH + kbase + (size_t)(t + NWAVES) * 32 * IDD, KIL + kbase + (size_t)(t + NWAVES) * 32 * IDD);
;         float sa[2], sb[2]; idx_tile(qa, k, sa); idx_tile(qb, k, sb);
;         const int col = t * 32 + r;
;         sc[(2 * kh) * SCP_LD + col] = sa[0]; sc[(2 * kh + 1) * SCP_LD + col] = sa[1];
;         sc[(4 + 2 * kh) * SCP_LD + col] = sb[0]; sc[(5 + 2 * kh) * SCP_LD + col] = sb[1];
;     }
;     __syncthreads();
.LidxA_go_3:
	v_mfma_f32_32x32x16_bf16 v[2:17], v[18:21], v[160:163], 0
	v_mfma_f32_32x32x16_bf16 v[2:17], v[22:25], v[164:167], v[2:17]
	v_mfma_f32_32x32x16_bf16 v[2:17], v[26:29], v[168:171], v[2:17]
	v_mfma_f32_32x32x16_bf16 v[2:17], v[30:33], v[172:175], v[2:17]
	s_nop 11
	v_mul_f32_e32 v82, 0x3e000000, v2
	v_max_f32_e32 v82, 0, v82
	v_fma_f32 v86, v50, v82, 0
	v_mul_f32_e32 v83, 0x3e000000, v3
	v_max_f32_e32 v83, 0, v83
	v_fmac_f32_e32 v86, v51, v83
	v_mul_f32_e32 v82, 0x3e000000, v4
	v_max_f32_e32 v82, 0, v82
	v_fmac_f32_e32 v86, v52, v82
	v_mul_f32_e32 v83, 0x3e000000, v5
	v_max_f32_e32 v83, 0, v83
	v_fmac_f32_e32 v86, v53, v83
	v_mul_f32_e32 v82, 0x3e000000, v6
	v_max_f32_e32 v82, 0, v82
	v_fmac_f32_e32 v86, v54, v82
	v_mul_f32_e32 v83, 0x3e000000, v7
	v_max_f32_e32 v83, 0, v83
	v_fmac_f32_e32 v86, v55, v83
	v_mul_f32_e32 v82, 0x3e000000, v8
	v_max_f32_e32 v82, 0, v82
	v_fmac_f32_e32 v86, v56, v82
	v_mul_f32_e32 v83, 0x3e000000, v9
	v_max_f32_e32 v83, 0, v83
	v_fmac_f32_e32 v86, v57, v83
	v_mul_f32_e32 v82, 0x3e000000, v10
	v_max_f32_e32 v82, 0, v82
	v_fma_f32 v87, v58, v82, 0
	v_mul_f32_e32 v83, 0x3e000000, v11
	v_max_f32_e32 v83, 0, v83
	v_fmac_f32_e32 v87, v59, v83
	v_mul_f32_e32 v82, 0x3e000000, v12
	v_max_f32_e32 v82, 0, v82
	v_fmac_f32_e32 v87, v60, v82
	v_mul_f32_e32 v83, 0x3e000000, v13
	v_max_f32_e32 v83, 0, v83
	v_fmac_f32_e32 v87, v61, v83
	v_mul_f32_e32 v82, 0x3e000000, v14
	v_max_f32_e32 v82, 0, v82
	v_fmac_f32_e32 v87, v62, v82
	v_mul_f32_e32 v83, 0x3e000000, v15
	v_max_f32_e32 v83, 0, v83
	v_fmac_f32_e32 v87, v63, v83
	v_mul_f32_e32 v82, 0x3e000000, v16
	v_max_f32_e32 v82, 0, v82
	v_fmac_f32_e32 v87, v64, v82
	v_mul_f32_e32 v83, 0x3e000000, v17
	v_max_f32_e32 v83, 0, v83
	v_fmac_f32_e32 v87, v65, v83
	v_mfma_f32_32x32x16_bf16 v[2:17], v[34:37], v[160:163], 0
	v_mfma_f32_32x32x16_bf16 v[2:17], v[38:41], v[164:167], v[2:17]
	v_mfma_f32_32x32x16_bf16 v[2:17], v[42:45], v[168:171], v[2:17]
	v_mfma_f32_32x32x16_bf16 v[2:17], v[46:49], v[172:175], v[2:17]
	s_add_i32 s1, s5, 4
	s_cmp_lt_u32 s1, s3
	s_cbranch_scc0 .LidxA_nr_3
	global_load_dwordx4 v[160:163], v95, s[6:7]
	global_load_dwordx4 v[164:167], v95, s[6:7] offset:32
	global_load_dwordx4 v[168:171], v95, s[6:7] offset:64
	global_load_dwordx4 v[172:175], v95, s[6:7] offset:96
	v_add_u32_e32 v95, 0x8000, v95
.LidxA_nr_3:
	s_nop 8
	v_mul_f32_e32 v82, 0x3e000000, v2
	v_max_f32_e32 v82, 0, v82
	v_fma_f32 v88, v66, v82, 0
	v_mul_f32_e32 v83, 0x3e000000, v3
	v_max_f32_e32 v83, 0, v83
	v_fmac_f32_e32 v88, v67, v83
	v_mul_f32_e32 v82, 0x3e000000, v4
	v_max_f32_e32 v82, 0, v82
	v_fmac_f32_e32 v88, v68, v82
	v_mul_f32_e32 v83, 0x3e000000, v5
	v_max_f32_e32 v83, 0, v83
	v_fmac_f32_e32 v88, v69, v83
	v_mul_f32_e32 v82, 0x3e000000, v6
	v_max_f32_e32 v82, 0, v82
	v_fmac_f32_e32 v88, v70, v82
	v_mul_f32_e32 v83, 0x3e000000, v7
	v_max_f32_e32 v83, 0, v83
	v_fmac_f32_e32 v88, v71, v83
	v_mul_f32_e32 v82, 0x3e000000, v8
	v_max_f32_e32 v82, 0, v82
	v_fmac_f32_e32 v88, v72, v82
	v_mul_f32_e32 v83, 0x3e000000, v9
	v_max_f32_e32 v83, 0, v83
	v_fmac_f32_e32 v88, v73, v83
	v_mul_f32_e32 v82, 0x3e000000, v10
	v_max_f32_e32 v82, 0, v82
	v_fma_f32 v89, v74, v82, 0
	v_mul_f32_e32 v83, 0x3e000000, v11
	v_max_f32_e32 v83, 0, v83
	v_fmac_f32_e32 v89, v75, v83
	v_mul_f32_e32 v82, 0x3e000000, v12
	v_max_f32_e32 v82, 0, v82
	v_fmac_f32_e32 v89, v76, v82
	v_mul_f32_e32 v83, 0x3e000000, v13
	v_max_f32_e32 v83, 0, v83
	v_fmac_f32_e32 v89, v77, v83
	v_mul_f32_e32 v82, 0x3e000000, v14
	v_max_f32_e32 v82, 0, v82
	v_fmac_f32_e32 v89, v78, v82
	v_mul_f32_e32 v83, 0x3e000000, v15
	v_max_f32_e32 v83, 0, v83
	v_fmac_f32_e32 v89, v79, v83
	v_mul_f32_e32 v82, 0x3e000000, v16
	v_max_f32_e32 v82, 0, v82
	v_fmac_f32_e32 v89, v80, v82
	v_mul_f32_e32 v83, 0x3e000000, v17
	v_max_f32_e32 v83, 0, v83
	v_fmac_f32_e32 v89, v81, v83
	v_add_u32_e32 v93, 0xffff0000, v92
	ds_write_b32 v93, v86
	v_add_u32_e32 v93, 0xffff4000, v92
	ds_write_b32 v93, v87
	ds_write2st64_b32 v92, v88, v89 offset1:64
	v_add_u32_e32 v92, 0x400, v92
	s_add_i32 s5, s5, 1
	s_cmp_lt_u32 s5, s3
	s_cbranch_scc0 .LidxA_done
	s_branch .LidxA_slot_0
.LidxA_done:
.LBB0_879:
	s_lshl_b32 s0, s4, 14
	s_add_i32 s1, s0, 0
	v_lshl_add_u32 v2, v84, 2, s1
	s_waitcnt lgkmcnt(0)
	s_barrier
; #define PG8_LAS __attribute__((address_space(3)))
; __device__ __forceinline__ unsigned fkey(float f) { const unsigned u = __float_as_uint(f); return (u & 0x80000000u) ? ~u : (u | 0x80000000u); }
;     constexpr int NG = (NJ + 7) / 8;
;     unsigned v[NJ];
;     const int nj = __builtin_amdgcn_readfirstlane((n + 63) >> 6), ng = (nj + 7) >> 3;
;     const PG8_LAS float* pl = sc + lane;
; #pragma unroll
;     for (int j = 0; j < NJ; ++j) { const unsigned k = fkey(pl[j * 64]); v[j] = (lane < n - j * 64) ? k : 0u; }
	ds_read2st64_b32 v[4:5], v2 offset1:1
	s_add_i32 s0, s4, s10
	ds_read2st64_b32 v[8:9], v2 offset0:2 offset1:3
	ds_read2st64_b32 v[10:11], v2 offset0:4 offset1:5
	ds_read2st64_b32 v[12:13], v2 offset0:6 offset1:7
	s_add_i32 s3, s0, 64
	s_ashr_i32 s5, s3, 6
	s_waitcnt lgkmcnt(3)
	v_not_b32_e32 v3, v4
	v_or_b32_e32 v6, 0x80000000, v4
	v_cmp_gt_i32_e32 vcc, 0, v4
	s_sub_i32 s3, s0, 63
	s_waitcnt lgkmcnt(2)
	v_and_b32_e32 v15, 0x7fffffff, v8
	v_cndmask_b32_e32 v3, v6, v3, vcc
	v_cmp_ge_i32_e32 vcc, s0, v84
	v_or_b32_e32 v6, 0x80000000, v5
	v_and_b32_e32 v14, 0x7fffffff, v9
	v_cndmask_b32_e32 v4, 0, v3, vcc
	v_not_b32_e32 v3, v5
	v_cmp_gt_i32_e32 vcc, 0, v5
	v_xor_b32_e32 v5, -1, v9
	v_pk_add_f32 v[14:15], v[14:15], 0 neg_lo:[1,1] neg_hi:[1,1]
	v_cndmask_b32_e32 v3, v6, v3, vcc
	v_cmp_gt_i32_e32 vcc, s3, v84
	s_add_i32 s3, s0, 0xffffff81
	s_add_i32 s6, s0, 0xffffff41
	v_cndmask_b32_e32 v6, 0, v3, vcc
	v_cmp_gt_i32_e32 vcc, 0, v9
	v_xor_b32_e32 v3, -1, v8
	s_waitcnt lgkmcnt(1)
	v_xor_b32_e32 v7, -1, v11
	v_cndmask_b32_e32 v5, v14, v5, vcc
	v_cmp_gt_i32_e32 vcc, 0, v8
	v_and_b32_e32 v14, 0x7fffffff, v11
	s_add_i32 s1, s5, 7
	v_cndmask_b32_e32 v3, v15, v3, vcc
	v_cmp_gt_i32_e32 vcc, s3, v84
	v_and_b32_e32 v15, 0x7fffffff, v10
	v_pk_add_f32 v[14:15], v[14:15], 0 neg_lo:[1,1] neg_hi:[1,1]
	v_cndmask_b32_e32 v9, 0, v3, vcc
	v_cmp_gt_i32_e32 vcc, s6, v84
	v_xor_b32_e32 v3, -1, v10
	s_add_i32 s3, s0, 0xffffff01
	v_cndmask_b32_e32 v5, 0, v5, vcc
	v_cmp_gt_i32_e32 vcc, 0, v11
	s_add_i32 s6, s0, 0xfffffec1
	s_waitcnt lgkmcnt(0)
	v_and_b32_e32 v11, 0x7fffffff, v12
	v_cndmask_b32_e32 v7, v14, v7, vcc
	v_cmp_gt_i32_e32 vcc, 0, v10
	v_and_b32_e32 v10, 0x7fffffff, v13
	v_xor_b32_e32 v14, -1, v13
	v_cndmask_b32_e32 v3, v15, v3, vcc
	v_cmp_gt_i32_e32 vcc, s3, v84
	v_pk_add_f32 v[10:11], v[10:11], 0 neg_lo:[1,1] neg_hi:[1,1]
	s_add_i32 s3, s0, 0xfffffe81
	v_cndmask_b32_e32 v8, 0, v3, vcc
	v_cmp_gt_i32_e32 vcc, s6, v84
	s_add_i32 s6, s0, 0xfffffe41
	s_ashr_i32 s13, s1, 3
	v_cndmask_b32_e32 v3, 0, v7, vcc
	v_cmp_gt_i32_e32 vcc, 0, v13
	v_xor_b32_e32 v7, -1, v12
	s_nop 0
	v_cndmask_b32_e32 v14, v10, v14, vcc
	v_cmp_gt_i32_e32 vcc, 0, v12
	ds_read2st64_b32 v[12:13], v2 offset0:8 offset1:9
	s_waitcnt lgkmcnt(0)
	v_and_b32_e32 v17, 0x7fffffff, v12
	v_cndmask_b32_e32 v7, v11, v7, vcc
	v_cmp_gt_i32_e32 vcc, s3, v84
	v_and_b32_e32 v16, 0x7fffffff, v13
	v_xor_b32_e32 v22, -1, v13
	v_cndmask_b32_e32 v10, 0, v7, vcc
	v_cmp_gt_i32_e32 vcc, s6, v84
	v_pk_add_f32 v[16:17], v[16:17], 0 neg_lo:[1,1] neg_hi:[1,1]
	v_xor_b32_e32 v11, -1, v12
	v_cndmask_b32_e32 v7, 0, v14, vcc
	ds_read2st64_b32 v[14:15], v2 offset0:10 offset1:11
	ds_read2st64_b32 v[18:19], v2 offset0:12 offset1:13
	ds_read2st64_b32 v[20:21], v2 offset0:14 offset1:15
	v_cmp_gt_i32_e32 vcc, 0, v13
	s_add_i32 s3, s0, 0xfffffe01
	s_add_i32 s6, s0, 0xfffffdc1
	v_cndmask_b32_e32 v13, v16, v22, vcc
	v_cmp_gt_i32_e32 vcc, 0, v12
	s_waitcnt lgkmcnt(2)
	v_and_b32_e32 v23, 0x7fffffff, v14
	v_and_b32_e32 v22, 0x7fffffff, v15
	v_cndmask_b32_e32 v11, v17, v11, vcc
	v_cmp_gt_i32_e32 vcc, s3, v84
	v_xor_b32_e32 v12, -1, v15
	v_pk_add_f32 v[22:23], v[22:23], 0 neg_lo:[1,1] neg_hi:[1,1]
	v_cndmask_b32_e32 v17, 0, v11, vcc
	v_cmp_gt_i32_e32 vcc, s6, v84
	v_xor_b32_e32 v11, -1, v14
	s_add_i32 s3, s0, 0xfffffd81
	v_cndmask_b32_e32 v13, 0, v13, vcc
	v_cmp_gt_i32_e32 vcc, 0, v15
	s_add_i32 s6, s0, 0xfffffd41
	s_waitcnt lgkmcnt(1)
	v_and_b32_e32 v15, 0x7fffffff, v18
	v_cndmask_b32_e32 v12, v22, v12, vcc
	v_cmp_gt_i32_e32 vcc, 0, v14
	v_and_b32_e32 v14, 0x7fffffff, v19
	v_xor_b32_e32 v22, -1, v19
	v_cndmask_b32_e32 v11, v23, v11, vcc
	v_cmp_gt_i32_e32 vcc, s3, v84
	v_pk_add_f32 v[14:15], v[14:15], 0 neg_lo:[1,1] neg_hi:[1,1]
	s_add_i32 s3, s0, 0xfffffd01
	v_cndmask_b32_e32 v16, 0, v11, vcc
	v_cmp_gt_i32_e32 vcc, s6, v84
	v_xor_b32_e32 v11, -1, v18
	s_add_i32 s6, s0, 0xfffffcc1
	v_cndmask_b32_e32 v12, 0, v12, vcc
	v_cmp_gt_i32_e32 vcc, 0, v19
	s_waitcnt lgkmcnt(0)
	v_and_b32_e32 v19, 0x7fffffff, v20
	v_cndmask_b32_e32 v14, v14, v22, vcc
	v_cmp_gt_i32_e32 vcc, 0, v18
	v_and_b32_e32 v18, 0x7fffffff, v21
	v_xor_b32_e32 v22, -1, v21
	v_cndmask_b32_e32 v11, v15, v11, vcc
	v_cmp_gt_i32_e32 vcc, s3, v84
	v_pk_add_f32 v[18:19], v[18:19], 0 neg_lo:[1,1] neg_hi:[1,1]
	s_add_i32 s3, s0, 0xfffffc81
	v_cndmask_b32_e32 v15, 0, v11, vcc
	v_cmp_gt_i32_e32 vcc, s6, v84
	s_add_i32 s6, s0, 0xfffffc41
	s_nop 0
	v_cndmask_b32_e32 v11, 0, v14, vcc
	v_cmp_gt_i32_e32 vcc, 0, v21
	v_xor_b32_e32 v14, -1, v20
	s_nop 0
	v_cndmask_b32_e32 v22, v18, v22, vcc
	v_cmp_gt_i32_e32 vcc, 0, v20
	ds_read2st64_b32 v[20:21], v2 offset0:16 offset1:17
	s_waitcnt lgkmcnt(0)
	v_and_b32_e32 v25, 0x7fffffff, v20
	v_cndmask_b32_e32 v14, v19, v14, vcc
	v_cmp_gt_i32_e32 vcc, s3, v84
	v_and_b32_e32 v24, 0x7fffffff, v21
	v_xor_b32_e32 v30, -1, v21
	v_cndmask_b32_e32 v18, 0, v14, vcc
	v_cmp_gt_i32_e32 vcc, s6, v84
	v_pk_add_f32 v[24:25], v[24:25], 0 neg_lo:[1,1] neg_hi:[1,1]
	v_xor_b32_e32 v19, -1, v20
	v_cndmask_b32_e32 v14, 0, v22, vcc
	ds_read2st64_b32 v[22:23], v2 offset0:18 offset1:19
	ds_read2st64_b32 v[26:27], v2 offset0:20 offset1:21
	ds_read2st64_b32 v[28:29], v2 offset0:22 offset1:23
	v_cmp_gt_i32_e32 vcc, 0, v21
	s_add_i32 s3, s0, 0xfffffc01
	s_add_i32 s6, s0, 0xfffffbc1
	v_cndmask_b32_e32 v21, v24, v30, vcc
	v_cmp_gt_i32_e32 vcc, 0, v20
	s_waitcnt lgkmcnt(2)
	v_and_b32_e32 v31, 0x7fffffff, v22
	v_and_b32_e32 v30, 0x7fffffff, v23
	v_cndmask_b32_e32 v19, v25, v19, vcc
	v_cmp_gt_i32_e32 vcc, s3, v84
	v_xor_b32_e32 v20, -1, v23
	v_pk_add_f32 v[30:31], v[30:31], 0 neg_lo:[1,1] neg_hi:[1,1]
	v_cndmask_b32_e32 v25, 0, v19, vcc
	v_cmp_gt_i32_e32 vcc, s6, v84
	v_xor_b32_e32 v19, -1, v22
	s_add_i32 s3, s0, 0xfffffb81
	v_cndmask_b32_e32 v21, 0, v21, vcc
	v_cmp_gt_i32_e32 vcc, 0, v23
	s_add_i32 s6, s0, 0xfffffb41
	s_waitcnt lgkmcnt(1)
; #define PG8_LAS __attribute__((address_space(3)))
; __device__ __forceinline__ unsigned fkey(float f) { const unsigned u = __float_as_uint(f); return (u & 0x80000000u) ? ~u : (u | 0x80000000u); }
;     constexpr int NG = (NJ + 7) / 8;
;     unsigned v[NJ];
;     const int nj = __builtin_amdgcn_readfirstlane((n + 63) >> 6), ng = (nj + 7) >> 3;
;     const PG8_LAS float* pl = sc + lane;
; #pragma unroll
;     for (int j = 0; j < NJ; ++j) { const unsigned k = fkey(pl[j * 64]); v[j] = (lane < n - j * 64) ? k : 0u; }
	v_and_b32_e32 v23, 0x7fffffff, v26
	v_cndmask_b32_e32 v20, v30, v20, vcc
	v_cmp_gt_i32_e32 vcc, 0, v22
	v_and_b32_e32 v22, 0x7fffffff, v27
	v_xor_b32_e32 v30, -1, v27
	v_cndmask_b32_e32 v19, v31, v19, vcc
	v_cmp_gt_i32_e32 vcc, s3, v84
	v_pk_add_f32 v[22:23], v[22:23], 0 neg_lo:[1,1] neg_hi:[1,1]
	s_add_i32 s3, s0, 0xfffffb01
	v_cndmask_b32_e32 v24, 0, v19, vcc
	v_cmp_gt_i32_e32 vcc, s6, v84
	v_xor_b32_e32 v19, -1, v26
	s_add_i32 s6, s0, 0xfffffac1
	v_cndmask_b32_e32 v20, 0, v20, vcc
	v_cmp_gt_i32_e32 vcc, 0, v27
	s_waitcnt lgkmcnt(0)
	v_and_b32_e32 v27, 0x7fffffff, v28
	v_cndmask_b32_e32 v22, v22, v30, vcc
	v_cmp_gt_i32_e32 vcc, 0, v26
	v_and_b32_e32 v26, 0x7fffffff, v29
	v_xor_b32_e32 v30, -1, v29
	v_cndmask_b32_e32 v19, v23, v19, vcc
	v_cmp_gt_i32_e32 vcc, s3, v84
	v_pk_add_f32 v[26:27], v[26:27], 0 neg_lo:[1,1] neg_hi:[1,1]
	s_add_i32 s3, s0, 0xfffffa81
	v_cndmask_b32_e32 v23, 0, v19, vcc
	v_cmp_gt_i32_e32 vcc, s6, v84
	s_add_i32 s6, s0, 0xfffffa41
	s_nop 0
	v_cndmask_b32_e32 v19, 0, v22, vcc
	v_cmp_gt_i32_e32 vcc, 0, v29
	v_xor_b32_e32 v22, -1, v28
	s_nop 0
	v_cndmask_b32_e32 v30, v26, v30, vcc
	v_cmp_gt_i32_e32 vcc, 0, v28
	ds_read2st64_b32 v[28:29], v2 offset0:24 offset1:25
	s_waitcnt lgkmcnt(0)
	v_and_b32_e32 v33, 0x7fffffff, v28
	v_cndmask_b32_e32 v22, v27, v22, vcc
	v_cmp_gt_i32_e32 vcc, s3, v84
	v_and_b32_e32 v32, 0x7fffffff, v29
	v_xor_b32_e32 v38, -1, v29
	v_cndmask_b32_e32 v26, 0, v22, vcc
	v_cmp_gt_i32_e32 vcc, s6, v84
	v_pk_add_f32 v[32:33], v[32:33], 0 neg_lo:[1,1] neg_hi:[1,1]
	v_xor_b32_e32 v27, -1, v28
	v_cndmask_b32_e32 v22, 0, v30, vcc
	ds_read2st64_b32 v[30:31], v2 offset0:26 offset1:27
	ds_read2st64_b32 v[34:35], v2 offset0:28 offset1:29
	ds_read2st64_b32 v[36:37], v2 offset0:30 offset1:31
	v_cmp_gt_i32_e32 vcc, 0, v29
	s_add_i32 s3, s0, 0xfffffa01
	s_add_i32 s6, s0, 0xfffff9c1
	v_cndmask_b32_e32 v29, v32, v38, vcc
	v_cmp_gt_i32_e32 vcc, 0, v28
	s_waitcnt lgkmcnt(2)
	v_and_b32_e32 v39, 0x7fffffff, v30
	v_and_b32_e32 v38, 0x7fffffff, v31
	v_cndmask_b32_e32 v27, v33, v27, vcc
	v_cmp_gt_i32_e32 vcc, s3, v84
	v_xor_b32_e32 v28, -1, v31
	v_pk_add_f32 v[38:39], v[38:39], 0 neg_lo:[1,1] neg_hi:[1,1]
	v_cndmask_b32_e32 v33, 0, v27, vcc
	v_cmp_gt_i32_e32 vcc, s6, v84
	v_xor_b32_e32 v27, -1, v30
	s_add_i32 s3, s0, 0xfffff981
	v_cndmask_b32_e32 v29, 0, v29, vcc
	v_cmp_gt_i32_e32 vcc, 0, v31
	s_add_i32 s6, s0, 0xfffff941
	s_waitcnt lgkmcnt(1)
	v_and_b32_e32 v31, 0x7fffffff, v34
	v_cndmask_b32_e32 v28, v38, v28, vcc
	v_cmp_gt_i32_e32 vcc, 0, v30
	v_and_b32_e32 v30, 0x7fffffff, v35
	v_xor_b32_e32 v38, -1, v35
	v_cndmask_b32_e32 v27, v39, v27, vcc
	v_cmp_gt_i32_e32 vcc, s3, v84
	v_pk_add_f32 v[30:31], v[30:31], 0 neg_lo:[1,1] neg_hi:[1,1]
	s_add_i32 s3, s0, 0xfffff901
	v_cndmask_b32_e32 v32, 0, v27, vcc
	v_cmp_gt_i32_e32 vcc, s6, v84
	v_xor_b32_e32 v27, -1, v34
	s_add_i32 s6, s0, 0xfffff8c1
	v_cndmask_b32_e32 v28, 0, v28, vcc
	v_cmp_gt_i32_e32 vcc, 0, v35
	s_waitcnt lgkmcnt(0)
	v_and_b32_e32 v35, 0x7fffffff, v36
	v_cndmask_b32_e32 v30, v30, v38, vcc
	v_cmp_gt_i32_e32 vcc, 0, v34
	v_and_b32_e32 v34, 0x7fffffff, v37
	v_xor_b32_e32 v38, -1, v37
	v_cndmask_b32_e32 v27, v31, v27, vcc
	v_cmp_gt_i32_e32 vcc, s3, v84
	v_pk_add_f32 v[34:35], v[34:35], 0 neg_lo:[1,1] neg_hi:[1,1]
	s_add_i32 s3, s0, 0xfffff881
	v_cndmask_b32_e32 v31, 0, v27, vcc
	v_cmp_gt_i32_e32 vcc, s6, v84
	s_add_i32 s6, s0, 0xfffff841
	s_nop 0
	v_cndmask_b32_e32 v27, 0, v30, vcc
	v_cmp_gt_i32_e32 vcc, 0, v37
	v_xor_b32_e32 v30, -1, v36
	s_nop 0
	v_cndmask_b32_e32 v38, v34, v38, vcc
	v_cmp_gt_i32_e32 vcc, 0, v36
	ds_read2st64_b32 v[36:37], v2 offset0:32 offset1:33
	s_waitcnt lgkmcnt(0)
	v_and_b32_e32 v41, 0x7fffffff, v36
	v_cndmask_b32_e32 v30, v35, v30, vcc
	v_cmp_gt_i32_e32 vcc, s3, v84
	v_and_b32_e32 v40, 0x7fffffff, v37
	v_xor_b32_e32 v46, -1, v37
	v_cndmask_b32_e32 v34, 0, v30, vcc
	v_cmp_gt_i32_e32 vcc, s6, v84
	v_pk_add_f32 v[40:41], v[40:41], 0 neg_lo:[1,1] neg_hi:[1,1]
	v_xor_b32_e32 v35, -1, v36
	v_cndmask_b32_e32 v30, 0, v38, vcc
	ds_read2st64_b32 v[38:39], v2 offset0:34 offset1:35
	ds_read2st64_b32 v[42:43], v2 offset0:36 offset1:37
	ds_read2st64_b32 v[44:45], v2 offset0:38 offset1:39
	v_cmp_gt_i32_e32 vcc, 0, v37
	s_add_i32 s3, s0, 0xfffff801
	s_add_i32 s6, s0, 0xfffff7c1
	v_cndmask_b32_e32 v37, v40, v46, vcc
	v_cmp_gt_i32_e32 vcc, 0, v36
	s_waitcnt lgkmcnt(2)
	v_and_b32_e32 v47, 0x7fffffff, v38
	v_and_b32_e32 v46, 0x7fffffff, v39
	v_cndmask_b32_e32 v35, v41, v35, vcc
	v_cmp_gt_i32_e32 vcc, s3, v84
	v_xor_b32_e32 v36, -1, v39
	v_pk_add_f32 v[46:47], v[46:47], 0 neg_lo:[1,1] neg_hi:[1,1]
	v_cndmask_b32_e32 v41, 0, v35, vcc
	v_cmp_gt_i32_e32 vcc, s6, v84
	v_xor_b32_e32 v35, -1, v38
	s_add_i32 s3, s0, 0xfffff781
	v_cndmask_b32_e32 v37, 0, v37, vcc
	v_cmp_gt_i32_e32 vcc, 0, v39
	s_add_i32 s6, s0, 0xfffff741
	s_waitcnt lgkmcnt(1)
	v_and_b32_e32 v39, 0x7fffffff, v42
	v_cndmask_b32_e32 v36, v46, v36, vcc
	v_cmp_gt_i32_e32 vcc, 0, v38
	v_and_b32_e32 v38, 0x7fffffff, v43
	v_xor_b32_e32 v46, -1, v43
	v_cndmask_b32_e32 v35, v47, v35, vcc
	v_cmp_gt_i32_e32 vcc, s3, v84
	v_pk_add_f32 v[38:39], v[38:39], 0 neg_lo:[1,1] neg_hi:[1,1]
	s_add_i32 s3, s0, 0xfffff701
	v_cndmask_b32_e32 v40, 0, v35, vcc
	v_cmp_gt_i32_e32 vcc, s6, v84
	v_xor_b32_e32 v35, -1, v42
	s_add_i32 s6, s0, 0xfffff6c1
	v_cndmask_b32_e32 v36, 0, v36, vcc
	v_cmp_gt_i32_e32 vcc, 0, v43
	s_waitcnt lgkmcnt(0)
; #define PG8_LAS __attribute__((address_space(3)))
; __device__ __forceinline__ unsigned fkey(float f) { const unsigned u = __float_as_uint(f); return (u & 0x80000000u) ? ~u : (u | 0x80000000u); }
;     constexpr int NG = (NJ + 7) / 8;
;     unsigned v[NJ];
;     const int nj = __builtin_amdgcn_readfirstlane((n + 63) >> 6), ng = (nj + 7) >> 3;
;     const PG8_LAS float* pl = sc + lane;
; #pragma unroll
;     for (int j = 0; j < NJ; ++j) { const unsigned k = fkey(pl[j * 64]); v[j] = (lane < n - j * 64) ? k : 0u; }
	v_and_b32_e32 v43, 0x7fffffff, v44
	v_cndmask_b32_e32 v38, v38, v46, vcc
	v_cmp_gt_i32_e32 vcc, 0, v42
	v_and_b32_e32 v42, 0x7fffffff, v45
	v_xor_b32_e32 v46, -1, v45
	v_cndmask_b32_e32 v35, v39, v35, vcc
	v_cmp_gt_i32_e32 vcc, s3, v84
	v_pk_add_f32 v[42:43], v[42:43], 0 neg_lo:[1,1] neg_hi:[1,1]
	s_add_i32 s3, s0, 0xfffff681
	v_cndmask_b32_e32 v39, 0, v35, vcc
	v_cmp_gt_i32_e32 vcc, s6, v84
	s_add_i32 s6, s0, 0xfffff641
	s_nop 0
	v_cndmask_b32_e32 v35, 0, v38, vcc
	v_cmp_gt_i32_e32 vcc, 0, v45
	v_xor_b32_e32 v38, -1, v44
	s_nop 0
	v_cndmask_b32_e32 v46, v42, v46, vcc
	v_cmp_gt_i32_e32 vcc, 0, v44
	ds_read2st64_b32 v[44:45], v2 offset0:40 offset1:41
	s_waitcnt lgkmcnt(0)
	v_and_b32_e32 v49, 0x7fffffff, v44
	v_cndmask_b32_e32 v38, v43, v38, vcc
	v_cmp_gt_i32_e32 vcc, s3, v84
	v_and_b32_e32 v48, 0x7fffffff, v45
	v_xor_b32_e32 v54, -1, v45
	v_cndmask_b32_e32 v42, 0, v38, vcc
	v_cmp_gt_i32_e32 vcc, s6, v84
	v_pk_add_f32 v[48:49], v[48:49], 0 neg_lo:[1,1] neg_hi:[1,1]
	v_xor_b32_e32 v43, -1, v44
	v_cndmask_b32_e32 v38, 0, v46, vcc
	ds_read2st64_b32 v[46:47], v2 offset0:42 offset1:43
	ds_read2st64_b32 v[50:51], v2 offset0:44 offset1:45
	ds_read2st64_b32 v[52:53], v2 offset0:46 offset1:47
	v_cmp_gt_i32_e32 vcc, 0, v45
	s_add_i32 s3, s0, 0xfffff601
	s_add_i32 s6, s0, 0xfffff5c1
	v_cndmask_b32_e32 v45, v48, v54, vcc
	v_cmp_gt_i32_e32 vcc, 0, v44
	s_waitcnt lgkmcnt(2)
	v_and_b32_e32 v55, 0x7fffffff, v46
	v_and_b32_e32 v54, 0x7fffffff, v47
	v_cndmask_b32_e32 v43, v49, v43, vcc
	v_cmp_gt_i32_e32 vcc, s3, v84
	v_xor_b32_e32 v44, -1, v47
	v_pk_add_f32 v[54:55], v[54:55], 0 neg_lo:[1,1] neg_hi:[1,1]
	v_cndmask_b32_e32 v49, 0, v43, vcc
	v_cmp_gt_i32_e32 vcc, s6, v84
	v_xor_b32_e32 v43, -1, v46
	s_add_i32 s3, s0, 0xfffff581
	v_cndmask_b32_e32 v45, 0, v45, vcc
	v_cmp_gt_i32_e32 vcc, 0, v47
	s_add_i32 s6, s0, 0xfffff541
	s_waitcnt lgkmcnt(1)
	v_and_b32_e32 v47, 0x7fffffff, v50
	v_cndmask_b32_e32 v44, v54, v44, vcc
	v_cmp_gt_i32_e32 vcc, 0, v46
	v_and_b32_e32 v46, 0x7fffffff, v51
	v_xor_b32_e32 v54, -1, v51
	v_cndmask_b32_e32 v43, v55, v43, vcc
	v_cmp_gt_i32_e32 vcc, s3, v84
	v_pk_add_f32 v[46:47], v[46:47], 0 neg_lo:[1,1] neg_hi:[1,1]
	s_add_i32 s3, s0, 0xfffff501
	v_cndmask_b32_e32 v48, 0, v43, vcc
	v_cmp_gt_i32_e32 vcc, s6, v84
	v_xor_b32_e32 v43, -1, v50
	s_add_i32 s6, s0, 0xfffff4c1
	v_cndmask_b32_e32 v44, 0, v44, vcc
	v_cmp_gt_i32_e32 vcc, 0, v51
	s_waitcnt lgkmcnt(0)
	v_and_b32_e32 v51, 0x7fffffff, v52
	v_cndmask_b32_e32 v46, v46, v54, vcc
	v_cmp_gt_i32_e32 vcc, 0, v50
	v_and_b32_e32 v50, 0x7fffffff, v53
	v_xor_b32_e32 v54, -1, v53
	v_cndmask_b32_e32 v43, v47, v43, vcc
	v_cmp_gt_i32_e32 vcc, s3, v84
	v_pk_add_f32 v[50:51], v[50:51], 0 neg_lo:[1,1] neg_hi:[1,1]
	s_add_i32 s3, s0, 0xfffff481
	v_cndmask_b32_e32 v47, 0, v43, vcc
	v_cmp_gt_i32_e32 vcc, s6, v84
	s_add_i32 s6, s0, 0xfffff441
	s_nop 0
	v_cndmask_b32_e32 v43, 0, v46, vcc
	v_cmp_gt_i32_e32 vcc, 0, v53
	v_xor_b32_e32 v46, -1, v52
	s_nop 0
	v_cndmask_b32_e32 v54, v50, v54, vcc
	v_cmp_gt_i32_e32 vcc, 0, v52
	ds_read2st64_b32 v[52:53], v2 offset0:48 offset1:49
	s_waitcnt lgkmcnt(0)
	v_and_b32_e32 v57, 0x7fffffff, v52
	v_cndmask_b32_e32 v46, v51, v46, vcc
	v_cmp_gt_i32_e32 vcc, s3, v84
	v_and_b32_e32 v56, 0x7fffffff, v53
	v_xor_b32_e32 v62, -1, v53
	v_cndmask_b32_e32 v50, 0, v46, vcc
	v_cmp_gt_i32_e32 vcc, s6, v84
	v_pk_add_f32 v[56:57], v[56:57], 0 neg_lo:[1,1] neg_hi:[1,1]
	v_xor_b32_e32 v51, -1, v52
	v_cndmask_b32_e32 v46, 0, v54, vcc
	ds_read2st64_b32 v[54:55], v2 offset0:50 offset1:51
	ds_read2st64_b32 v[58:59], v2 offset0:52 offset1:53
	ds_read2st64_b32 v[60:61], v2 offset0:54 offset1:55
	v_cmp_gt_i32_e32 vcc, 0, v53
	s_add_i32 s3, s0, 0xfffff401
	s_add_i32 s6, s0, 0xfffff3c1
	v_cndmask_b32_e32 v53, v56, v62, vcc
	v_cmp_gt_i32_e32 vcc, 0, v52
	s_waitcnt lgkmcnt(2)
	v_and_b32_e32 v63, 0x7fffffff, v54
	v_and_b32_e32 v62, 0x7fffffff, v55
	v_cndmask_b32_e32 v51, v57, v51, vcc
	v_cmp_gt_i32_e32 vcc, s3, v84
	v_xor_b32_e32 v52, -1, v55
	v_pk_add_f32 v[62:63], v[62:63], 0 neg_lo:[1,1] neg_hi:[1,1]
	v_cndmask_b32_e32 v57, 0, v51, vcc
	v_cmp_gt_i32_e32 vcc, s6, v84
	v_xor_b32_e32 v51, -1, v54
	s_add_i32 s3, s0, 0xfffff381
	v_cndmask_b32_e32 v53, 0, v53, vcc
	v_cmp_gt_i32_e32 vcc, 0, v55
	s_add_i32 s6, s0, 0xfffff341
	s_waitcnt lgkmcnt(1)
; #define PG8_LAS __attribute__((address_space(3)))
; __device__ __forceinline__ unsigned fkey(float f) { const unsigned u = __float_as_uint(f); return (u & 0x80000000u) ? ~u : (u | 0x80000000u); }
;     constexpr int NG = (NJ + 7) / 8;
;     unsigned v[NJ];
;     const int nj = __builtin_amdgcn_readfirstlane((n + 63) >> 6), ng = (nj + 7) >> 3;
;     const PG8_LAS float* pl = sc + lane;
; #pragma unroll
;     for (int j = 0; j < NJ; ++j) { const unsigned k = fkey(pl[j * 64]); v[j] = (lane < n - j * 64) ? k : 0u; }
;     unsigned T = 1u; int need = 1 << 30;
;     if (n > TOPK) {
;         unsigned prefix = 0u; bool exact;
;         if (NG >= 8 && ng > 7) exact = bit_search<(NG >= 8 ? 8 : NG), NJ, BITLO>(v, prefix);
;         else if (NG >= 7 && ng > 6) exact = bit_search<(NG >= 7 ? 7 : NG), NJ, BITLO>(v, prefix);
;         else if (NG >= 6 && ng > 5) exact = bit_search<(NG >= 6 ? 6 : NG), NJ, BITLO>(v, prefix);
;         else if (NG >= 5 && ng > 4) exact = bit_search<(NG >= 5 ? 5 : NG), NJ, BITLO>(v, prefix);
;         else if (NG >= 4 && ng > 3) exact = bit_search<(NG >= 4 ? 4 : NG), NJ, BITLO>(v, prefix);
;         else if (NG >= 3 && ng > 2) exact = bit_search<(NG >= 3 ? 3 : NG), NJ, BITLO>(v, prefix);
;         else if (NG >= 2 && ng > 1) exact = bit_search<(NG >= 2 ? 2 : NG), NJ, BITLO>(v, prefix);
;         else exact = bit_search<1, NJ, BITLO>(v, prefix);
	v_and_b32_e32 v55, 0x7fffffff, v58
	v_cndmask_b32_e32 v52, v62, v52, vcc
	v_cmp_gt_i32_e32 vcc, 0, v54
	v_and_b32_e32 v54, 0x7fffffff, v59
	v_xor_b32_e32 v62, -1, v59
	v_cndmask_b32_e32 v51, v63, v51, vcc
	v_cmp_gt_i32_e32 vcc, s3, v84
	v_pk_add_f32 v[54:55], v[54:55], 0 neg_lo:[1,1] neg_hi:[1,1]
	s_add_i32 s3, s0, 0xfffff301
	v_cndmask_b32_e32 v56, 0, v51, vcc
	v_cmp_gt_i32_e32 vcc, s6, v84
	v_xor_b32_e32 v51, -1, v58
	s_add_i32 s6, s0, 0xfffff2c1
	v_cndmask_b32_e32 v52, 0, v52, vcc
	v_cmp_gt_i32_e32 vcc, 0, v59
	s_waitcnt lgkmcnt(0)
	v_and_b32_e32 v59, 0x7fffffff, v60
	v_cndmask_b32_e32 v54, v54, v62, vcc
	v_cmp_gt_i32_e32 vcc, 0, v58
	v_and_b32_e32 v58, 0x7fffffff, v61
	v_xor_b32_e32 v62, -1, v61
	v_cndmask_b32_e32 v51, v55, v51, vcc
	v_cmp_gt_i32_e32 vcc, s3, v84
	v_pk_add_f32 v[58:59], v[58:59], 0 neg_lo:[1,1] neg_hi:[1,1]
	s_add_i32 s3, s0, 0xfffff281
	v_cndmask_b32_e32 v55, 0, v51, vcc
	v_cmp_gt_i32_e32 vcc, s6, v84
	s_add_i32 s6, s0, 0xfffff241
	s_nop 0
	v_cndmask_b32_e32 v51, 0, v54, vcc
	v_cmp_gt_i32_e32 vcc, 0, v61
	v_xor_b32_e32 v54, -1, v60
	s_nop 0
	v_cndmask_b32_e32 v62, v58, v62, vcc
	v_cmp_gt_i32_e32 vcc, 0, v60
	ds_read2st64_b32 v[60:61], v2 offset0:56 offset1:57
	s_waitcnt lgkmcnt(0)
	v_and_b32_e32 v65, 0x7fffffff, v60
	v_cndmask_b32_e32 v54, v59, v54, vcc
	v_cmp_gt_i32_e32 vcc, s3, v84
	v_and_b32_e32 v64, 0x7fffffff, v61
	v_xor_b32_e32 v59, -1, v61
	v_cndmask_b32_e32 v58, 0, v54, vcc
	v_cmp_gt_i32_e32 vcc, s6, v84
	v_pk_add_f32 v[64:65], v[64:65], 0 neg_lo:[1,1] neg_hi:[1,1]
	s_add_i32 s3, s0, 0xfffff201
	v_cndmask_b32_e32 v54, 0, v62, vcc
	ds_read2st64_b32 v[62:63], v2 offset0:58 offset1:59
	ds_read2st64_b32 v[66:67], v2 offset0:60 offset1:61
	ds_read2st64_b32 v[68:69], v2 offset0:62 offset1:63
	v_cmp_gt_i32_e32 vcc, 0, v61
	v_xor_b32_e32 v2, -1, v60
	s_add_i32 s6, s0, 0xfffff1c1
	v_cndmask_b32_e32 v59, v64, v59, vcc
	v_cmp_gt_i32_e32 vcc, 0, v60
	s_waitcnt lgkmcnt(2)
	v_and_b32_e32 v71, 0x7fffffff, v62
	v_and_b32_e32 v70, 0x7fffffff, v63
	v_cndmask_b32_e32 v2, v65, v2, vcc
	v_cmp_gt_i32_e32 vcc, s3, v84
	v_pk_add_f32 v[70:71], v[70:71], 0 neg_lo:[1,1] neg_hi:[1,1]
	s_add_i32 s3, s0, 0xfffff181
	v_cndmask_b32_e32 v65, 0, v2, vcc
	v_cmp_gt_i32_e32 vcc, s6, v84
	v_xor_b32_e32 v2, -1, v62
	s_add_i32 s6, s0, 0xfffff141
	v_cndmask_b32_e32 v61, 0, v59, vcc
	v_xor_b32_e32 v59, -1, v63
	v_cmp_gt_i32_e32 vcc, 0, v63
	s_waitcnt lgkmcnt(1)
	v_and_b32_e32 v63, 0x7fffffff, v66
	v_cndmask_b32_e32 v59, v70, v59, vcc
	v_cmp_gt_i32_e32 vcc, 0, v62
	v_and_b32_e32 v62, 0x7fffffff, v67
	v_pk_add_f32 v[62:63], v[62:63], 0 neg_lo:[1,1] neg_hi:[1,1]
	v_cndmask_b32_e32 v2, v71, v2, vcc
	v_cmp_gt_i32_e32 vcc, s3, v84
	s_add_i32 s3, s0, 0xfffff101
	s_nop 0
	v_cndmask_b32_e32 v64, 0, v2, vcc
	v_cmp_gt_i32_e32 vcc, s6, v84
	v_xor_b32_e32 v2, -1, v66
	s_add_i32 s6, s0, 0xfffff0c1
	v_cndmask_b32_e32 v60, 0, v59, vcc
	v_xor_b32_e32 v59, -1, v67
	v_cmp_gt_i32_e32 vcc, 0, v67
	s_waitcnt lgkmcnt(0)
	v_and_b32_e32 v67, 0x7fffffff, v68
	v_cndmask_b32_e32 v59, v62, v59, vcc
	v_cmp_gt_i32_e32 vcc, 0, v66
	v_and_b32_e32 v66, 0x7fffffff, v69
	v_pk_add_f32 v[66:67], v[66:67], 0 neg_lo:[1,1] neg_hi:[1,1]
	v_cndmask_b32_e32 v2, v63, v2, vcc
	v_cmp_gt_i32_e32 vcc, s3, v84
	v_xor_b32_e32 v63, -1, v69
	s_add_i32 s3, s0, 0xfffff081
	v_cndmask_b32_e32 v62, 0, v2, vcc
	v_cmp_gt_i32_e32 vcc, s6, v84
	v_xor_b32_e32 v2, -1, v68
	s_add_i32 s6, s0, 0xfffff041
	v_cndmask_b32_e32 v59, 0, v59, vcc
	v_cmp_gt_i32_e32 vcc, 0, v69
	s_cmpk_lt_i32 s0, 0x100
	s_nop 0
	v_cndmask_b32_e32 v63, v66, v63, vcc
	v_cmp_gt_i32_e32 vcc, 0, v68
	s_nop 1
	v_cndmask_b32_e32 v2, v67, v2, vcc
	v_cmp_gt_i32_e32 vcc, s3, v84
	s_nop 1
	v_cndmask_b32_e32 v66, 0, v2, vcc
	v_cmp_gt_i32_e32 vcc, s6, v84
	s_nop 1
	v_cndmask_b32_e32 v63, 0, v63, vcc
	s_cbranch_scc1 .LBB0_890
	s_cmp_gt_i32 s13, 7
	s_cselect_b64 s[0:1], -1, 0
	s_cmp_lt_i32 s13, 8
	s_cbranch_scc0 .LBB0_891
	s_cmp_lg_u32 s13, 7
	s_cbranch_scc0 .LBB0_892
	s_cmp_lt_i32 s13, 6
	s_cbranch_scc0 .LBB0_893
	s_cmp_lg_u32 s13, 5
	s_cbranch_scc0 .LBB0_894
	s_cmp_lt_i32 s13, 4
	s_cbranch_scc0 .LBB0_895
	s_cmp_lg_u32 s13, 3
	s_cbranch_scc0 .LBB0_896
	s_cmp_gt_i32 s13, 1
	s_cbranch_scc1 .LBB0_897
	v_mov_b32_e32 v2, 31
	v_mov_b32_e32 v67, 0

; #define PG8_LAS __attribute__((address_space(3)))
; __device__ __forceinline__ int fresh_tid() { int t = threadIdx.x; asm volatile("" : "+v"(t)); return t; }
;     const int tid_ = fresh_tid(), lane = tid_ & 63, wave = __builtin_amdgcn_readfirstlane(tid_ >> 6), r = lane & 31, kh = lane >> 5;
;     unsigned char* ws = p.ws;
;     const bf16_t* QI = (const bf16_t*)(ws + WS_QI); const float* WI = (const float*)(ws + WS_WI); unsigned long long* BM = (unsigned long long*)(ws + WS_BM);
;     const bf16_t* KIH = (const bf16_t*)(ws + WS_KIH); const bf16_t* KIL = (const bf16_t*)(ws + WS_KIL);
;     PG8_LAS float* sc = (PG8_LAS float*)lds;
;     const int b = s & 1, q0 = (s >> 1) * 8, grow0 = b * SEQ + q0, ntile = (q0 + 8 + 31) >> 5;
;     IdxQ qa, qb; idx_load_q(qa, QI, WI, grow0, lane); idx_load_q(qb, QI, WI, grow0 + 4, lane);
;     const size_t kbase = (size_t)(b * SEQ + r) * IDD + kh * 8;
;     IdxKey kn;
;     if (wave < ntile) idx_load_keyb(kn, KIH + kbase + (size_t)wave * 32 * IDD, KIL + kbase + (size_t)wave * 32 * IDD);
;     for (int t = wave; t < ntile; t += NWAVES) {
;         const IdxKey k = kn;
;         if (t + NWAVES < ntile) idx_load_keyb(kn, KIH + kbase + (size_t)(t + NWAVES) * 32 * IDD, KIL + kbase + (size_t)(t + NWAVES) * 32 * IDD);
;         float sa[2], sb[2]; idx_tile(qa, k, sa); idx_tile(qb, k, sb);
;         const int col = t * 32 + r;
;         sc[(2 * kh) * SCP_LD + col] = sa[0]; sc[(2 * kh + 1) * SCP_LD + col] = sa[1];
;         sc[(4 + 2 * kh) * SCP_LD + col] = sb[0]; sc[(5 + 2 * kh) * SCP_LD + col] = sb[1];
;     }
; __device__ __forceinline__ void mid1_phase(const Params& p, PG8_LAS unsigned char* lds) {
;     ...
;         if (idx >= NA + NC_ + NB2) break;
;         if (idx < NA) idx_sample_batch_unit(p, lds, (int)idx);
;         else if (idx < NA + NC_) { const unsigned g = idx - NA; lru_local_unit(p, lds, (int)(g & 7u), (LRU_NGRP - 1 - (int)(g >> 3)) * LRU_GRP); }
;         else { const int s2 = (int)(NB_ - 1 - 2 * (idx - NA - NC_)); idx_prompt_unit(p, lds, s2); __syncthreads(); idx_prompt_unit(p, lds, s2 - 1); }
.LBB0_1212:
	s_add_i32 s0, s4, s12
	s_ashr_i32 s1, s0, 31
	s_lshl_b64 s[0:1], s[0:1], 9
	v_readlane_b32 s3, v238, 3
	s_add_u32 s0, s3, s0
	v_readlane_b32 s3, v238, 4
	s_addc_u32 s1, s3, s1
	v_mov_b32_e32 v3, v68
	v_lshlrev_b32_e32 v4, 3, v84
	global_store_dwordx2 v4, v[2:3], s[0:1]
	v_mov_b32_e32 v2, v0
	s_barrier
	s_nop 0
	v_readfirstlane_b32 s0, v2
	s_ashr_i32 s0, s0, 6
	s_cmp_ge_i32 s0, s11
	v_and_b32_e32 v84, 63, v2
	s_cbranch_scc1 .LBB0_1217
	v_and_b32_e32 v3, 31, v2
	v_lshrrev_b32_e32 v5, 5, v84
	v_lshrrev_b32_e32 v4, 1, v84
	v_and_b32_e32 v6, 2, v4
	v_bfe_u32 v7, v2, 4, 1
	v_and_b32_e32 v8, 3, v2
	v_and_or_b32 v8, v4, 4, v8
	v_or3_b32 v9, s10, v7, v6
	v_lshlrev_b32_e32 v10, 10, v9
	v_lshl_add_u32 v10, v8, 7, v10
	v_lshl_add_u32 v10, v5, 4, v10
	v_add_u32_e32 v11, 0x1000, v10
	s_lshl_b32 s1, s10, 5
	v_lshl_add_u32 v12, v5, 6, s1
	global_load_dwordx4 v[18:21], v10, s[64:65]
	global_load_dwordx4 v[22:25], v10, s[64:65] offset:32
	global_load_dwordx4 v[26:29], v10, s[64:65] offset:64
	global_load_dwordx4 v[30:33], v10, s[64:65] offset:96
	global_load_dwordx4 v[34:37], v11, s[64:65]
	global_load_dwordx4 v[38:41], v11, s[64:65] offset:32
	global_load_dwordx4 v[42:45], v11, s[64:65] offset:64
	global_load_dwordx4 v[46:49], v11, s[64:65] offset:96
	global_load_dwordx4 v[50:53], v12, s[66:67]
	global_load_dwordx4 v[54:57], v12, s[66:67] offset:16
	global_load_dwordx4 v[58:61], v12, s[66:67] offset:32
	global_load_dwordx4 v[62:65], v12, s[66:67] offset:48
	global_load_dwordx4 v[66:69], v12, s[66:67] offset:128
	global_load_dwordx4 v[70:73], v12, s[66:67] offset:144
	global_load_dwordx4 v[74:77], v12, s[66:67] offset:160
	global_load_dwordx4 v[78:81], v12, s[66:67] offset:176
	s_add_u32 s6, s34, 0x22e82000
	s_addc_u32 s7, s35, 0
	s_lshl_b32 s1, s0, 12
	v_lshl_add_u32 v94, v3, 7, s1
	v_lshl_add_u32 v94, v5, 4, v94
	s_sub_i32 s3, s11, s0
	s_add_i32 s3, s3, 7
	s_lshr_b32 s3, s3, 3
	global_load_dwordx4 v[102:105], v94, s[6:7]
	global_load_dwordx4 v[106:109], v94, s[6:7] offset:32
	global_load_dwordx4 v[110:113], v94, s[6:7] offset:64
	global_load_dwordx4 v[114:117], v94, s[6:7] offset:96
	s_cmp_lt_u32 s3, 2
	s_cbranch_scc1 .LidxB_pd
	v_add_u32_e32 v95, 0x8000, v94
	global_load_dwordx4 v[118:121], v95, s[6:7]
	global_load_dwordx4 v[122:125], v95, s[6:7] offset:32
	global_load_dwordx4 v[126:129], v95, s[6:7] offset:64
	global_load_dwordx4 v[130:133], v95, s[6:7] offset:96
	s_cmp_lt_u32 s3, 3
	s_cbranch_scc1 .LidxB_pd
	v_add_u32_e32 v95, 0x10000, v94
	global_load_dwordx4 v[134:137], v95, s[6:7]
	global_load_dwordx4 v[138:141], v95, s[6:7] offset:32
	global_load_dwordx4 v[142:145], v95, s[6:7] offset:64
	global_load_dwordx4 v[146:149], v95, s[6:7] offset:96
	s_cmp_lt_u32 s3, 4
	s_cbranch_scc1 .LidxB_pd
	v_add_u32_e32 v95, 0x18000, v94
	global_load_dwordx4 v[160:163], v95, s[6:7]
	global_load_dwordx4 v[164:167], v95, s[6:7] offset:32
	global_load_dwordx4 v[168:171], v95, s[6:7] offset:64
	global_load_dwordx4 v[172:175], v95, s[6:7] offset:96
.LidxB_pd:
	v_add_u32_e32 v95, 0x20000, v94
	s_lshl_b32 s1, s0, 7
	v_lshl_add_u32 v92, v5, 15, s1
	v_lshl_add_u32 v92, v3, 2, v92
	v_add_u32_e32 v92, 0x10000, v92
	s_mov_b32 s5, 0
	s_sub_i32 s1, s3, s5
	s_cmp_gt_i32 s1, 3
	s_cbranch_scc1 .LidxB_w12_p
	s_cmp_eq_u32 s1, 3
	s_cbranch_scc1 .LidxB_w8_p
	s_cmp_eq_u32 s1, 2
	s_cbranch_scc1 .LidxB_w4_p
	s_waitcnt vmcnt(0)
	s_branch .LidxB_gp

; #define PG8_LAS __attribute__((address_space(3)))
; __device__ __forceinline__ unsigned fkey(float f) { const unsigned u = __float_as_uint(f); return (u & 0x80000000u) ? ~u : (u | 0x80000000u); }
;     constexpr int NG = (NJ + 7) / 8;
;     unsigned v[NJ];
;     const int nj = __builtin_amdgcn_readfirstlane((n + 63) >> 6), ng = (nj + 7) >> 3;
;     const PG8_LAS float* pl = sc + lane;
; #pragma unroll
;     for (int j = 0; j < NJ; ++j) { const unsigned k = fkey(pl[j * 64]); v[j] = (lane < n - j * 64) ? k : 0u; }
.LidxB_done:
.LBB0_1217:
	s_lshl_b32 s1, s0, 14
	s_add_i32 s1, s1, 0
	v_lshl_add_u32 v58, v84, 2, s1
	s_waitcnt lgkmcnt(0)
	s_barrier
	ds_read2st64_b32 v[4:5], v58 offset1:1
	s_add_i32 s4, s0, s10
	ds_read2st64_b32 v[6:7], v58 offset0:2 offset1:3
	ds_read2st64_b32 v[10:11], v58 offset0:4 offset1:5
	ds_read2st64_b32 v[12:13], v58 offset0:6 offset1:7
	s_sub_i32 s1, s4, 63
	s_add_i32 s3, s4, 0xffffff41
	s_waitcnt lgkmcnt(3)
	v_not_b32_e32 v2, v4
	v_or_b32_e32 v3, 0x80000000, v4
	v_cmp_gt_i32_e32 vcc, 0, v4
	v_or_b32_e32 v4, 0x80000000, v5
	s_waitcnt lgkmcnt(2)
	v_and_b32_e32 v9, 0x7fffffff, v6
	v_cndmask_b32_e32 v2, v3, v2, vcc
	v_cmp_ge_i32_e32 vcc, s4, v84
	v_and_b32_e32 v8, 0x7fffffff, v7
	v_pk_add_f32 v[8:9], v[8:9], 0 neg_lo:[1,1] neg_hi:[1,1]
	v_cndmask_b32_e32 v3, 0, v2, vcc
	v_not_b32_e32 v2, v5
	v_cmp_gt_i32_e32 vcc, 0, v5
	s_add_i32 s0, s4, 64
	s_ashr_i32 s5, s0, 6
	v_cndmask_b32_e32 v2, v4, v2, vcc
	v_cmp_gt_i32_e32 vcc, s1, v84
	v_xor_b32_e32 v4, -1, v7
	s_add_i32 s1, s4, 0xffffff81
	v_cndmask_b32_e32 v5, 0, v2, vcc
	v_cmp_gt_i32_e32 vcc, 0, v7
	v_xor_b32_e32 v2, -1, v6
	s_waitcnt lgkmcnt(1)
	v_and_b32_e32 v7, 0x7fffffff, v10
	v_cndmask_b32_e32 v4, v8, v4, vcc
	v_cmp_gt_i32_e32 vcc, 0, v6
	v_and_b32_e32 v6, 0x7fffffff, v11
	v_pk_add_f32 v[6:7], v[6:7], 0 neg_lo:[1,1] neg_hi:[1,1]
	v_cndmask_b32_e32 v2, v9, v2, vcc
	v_cmp_gt_i32_e32 vcc, s1, v84
	v_xor_b32_e32 v9, -1, v11
	s_add_i32 s1, s4, 0xffffff01
	v_cndmask_b32_e32 v8, 0, v2, vcc
	v_cmp_gt_i32_e32 vcc, s3, v84
	v_xor_b32_e32 v2, -1, v10
	s_add_i32 s3, s4, 0xfffffec1
	v_cndmask_b32_e32 v4, 0, v4, vcc
	v_cmp_gt_i32_e32 vcc, 0, v11
	s_waitcnt lgkmcnt(0)
	v_and_b32_e32 v11, 0x7fffffff, v12
	s_add_i32 s0, s5, 7
	v_cndmask_b32_e32 v6, v6, v9, vcc
	v_cmp_gt_i32_e32 vcc, 0, v10
	v_and_b32_e32 v10, 0x7fffffff, v13
	v_xor_b32_e32 v9, -1, v13
	v_cndmask_b32_e32 v2, v7, v2, vcc
	v_cmp_gt_i32_e32 vcc, s1, v84
	v_pk_add_f32 v[10:11], v[10:11], 0 neg_lo:[1,1] neg_hi:[1,1]
	s_add_i32 s1, s4, 0xfffffe81
	v_cndmask_b32_e32 v7, 0, v2, vcc
	v_cmp_gt_i32_e32 vcc, s3, v84
	s_add_i32 s3, s4, 0xfffffe41
	s_ashr_i32 s10, s0, 3
	v_cndmask_b32_e32 v2, 0, v6, vcc
	v_cmp_gt_i32_e32 vcc, 0, v13
	v_xor_b32_e32 v6, -1, v12
	s_nop 0
	v_cndmask_b32_e32 v13, v10, v9, vcc
	v_cmp_gt_i32_e32 vcc, 0, v12
	s_nop 1
	v_cndmask_b32_e32 v6, v11, v6, vcc
	ds_read2st64_b32 v[10:11], v58 offset0:8 offset1:9
	v_cmp_gt_i32_e32 vcc, s1, v84
	ds_read2st64_b32 v[14:15], v58 offset0:10 offset1:11
	ds_read2st64_b32 v[18:19], v58 offset0:12 offset1:13
	ds_read2st64_b32 v[20:21], v58 offset0:14 offset1:15
	v_cndmask_b32_e32 v9, 0, v6, vcc
	v_cmp_gt_i32_e32 vcc, s3, v84
	s_waitcnt lgkmcnt(3)
	v_and_b32_e32 v12, 0x7fffffff, v11
	v_xor_b32_e32 v17, -1, v11
	v_cndmask_b32_e32 v6, 0, v13, vcc
	v_and_b32_e32 v13, 0x7fffffff, v10
	v_pk_add_f32 v[12:13], v[12:13], 0 neg_lo:[1,1] neg_hi:[1,1]
	v_cmp_gt_i32_e32 vcc, 0, v11
	v_xor_b32_e32 v16, -1, v10
	s_add_i32 s1, s4, 0xfffffe01
	v_cndmask_b32_e32 v11, v12, v17, vcc
	v_cmp_gt_i32_e32 vcc, 0, v10
	s_add_i32 s3, s4, 0xfffffdc1
	s_waitcnt lgkmcnt(2)
	v_xor_b32_e32 v17, -1, v15
	v_cndmask_b32_e32 v10, v13, v16, vcc
	v_cmp_gt_i32_e32 vcc, s1, v84
	v_xor_b32_e32 v13, -1, v14
	s_add_i32 s1, s4, 0xfffffd81
	v_cndmask_b32_e32 v16, 0, v10, vcc
	v_cmp_gt_i32_e32 vcc, s3, v84
	v_and_b32_e32 v10, 0x7fffffff, v15
	s_add_i32 s3, s4, 0xfffffd41
	v_cndmask_b32_e32 v12, 0, v11, vcc
	v_and_b32_e32 v11, 0x7fffffff, v14
	v_pk_add_f32 v[10:11], v[10:11], 0 neg_lo:[1,1] neg_hi:[1,1]
	v_cmp_gt_i32_e32 vcc, 0, v15
	s_waitcnt lgkmcnt(1)
	v_and_b32_e32 v23, 0x7fffffff, v18
	v_and_b32_e32 v22, 0x7fffffff, v19
	v_cndmask_b32_e32 v10, v10, v17, vcc
	v_cmp_gt_i32_e32 vcc, 0, v14
	v_pk_add_f32 v[22:23], v[22:23], 0 neg_lo:[1,1] neg_hi:[1,1]
	s_waitcnt lgkmcnt(0)
	v_xor_b32_e32 v17, -1, v21
	v_cndmask_b32_e32 v11, v11, v13, vcc
	v_cmp_gt_i32_e32 vcc, s1, v84
	v_xor_b32_e32 v13, -1, v19
	s_add_i32 s1, s4, 0xfffffd01
	v_cndmask_b32_e32 v15, 0, v11, vcc
	v_cmp_gt_i32_e32 vcc, s3, v84
	s_add_i32 s3, s4, 0xfffffcc1
	s_nop 0
	v_cndmask_b32_e32 v11, 0, v10, vcc
	v_cmp_gt_i32_e32 vcc, 0, v19
	v_xor_b32_e32 v10, -1, v18
	v_and_b32_e32 v19, 0x7fffffff, v20
	v_cndmask_b32_e32 v13, v22, v13, vcc
	v_cmp_gt_i32_e32 vcc, 0, v18
	v_and_b32_e32 v18, 0x7fffffff, v21
	v_pk_add_f32 v[18:19], v[18:19], 0 neg_lo:[1,1] neg_hi:[1,1]
	v_cndmask_b32_e32 v10, v23, v10, vcc
	v_cmp_gt_i32_e32 vcc, s1, v84
	s_add_i32 s1, s4, 0xfffffc81
	s_nop 0
	v_cndmask_b32_e32 v14, 0, v10, vcc
	v_cmp_gt_i32_e32 vcc, s3, v84
	s_add_i32 s3, s4, 0xfffffc41
	s_nop 0
	v_cndmask_b32_e32 v10, 0, v13, vcc
	v_cmp_gt_i32_e32 vcc, 0, v21
	v_xor_b32_e32 v13, -1, v20
	s_nop 0
	v_cndmask_b32_e32 v21, v18, v17, vcc
	v_cmp_gt_i32_e32 vcc, 0, v20
	s_nop 1
	v_cndmask_b32_e32 v13, v19, v13, vcc
	ds_read2st64_b32 v[18:19], v58 offset0:16 offset1:17
	v_cmp_gt_i32_e32 vcc, s1, v84
	ds_read2st64_b32 v[22:23], v58 offset0:18 offset1:19
	ds_read2st64_b32 v[26:27], v58 offset0:20 offset1:21
	ds_read2st64_b32 v[28:29], v58 offset0:22 offset1:23
	v_cndmask_b32_e32 v17, 0, v13, vcc
	v_cmp_gt_i32_e32 vcc, s3, v84
	s_waitcnt lgkmcnt(3)
	v_and_b32_e32 v20, 0x7fffffff, v19
	v_xor_b32_e32 v25, -1, v19
	v_cndmask_b32_e32 v13, 0, v21, vcc
	v_and_b32_e32 v21, 0x7fffffff, v18
	v_pk_add_f32 v[20:21], v[20:21], 0 neg_lo:[1,1] neg_hi:[1,1]
	v_cmp_gt_i32_e32 vcc, 0, v19
	v_xor_b32_e32 v24, -1, v18
	s_add_i32 s1, s4, 0xfffffc01
	v_cndmask_b32_e32 v19, v20, v25, vcc
	v_cmp_gt_i32_e32 vcc, 0, v18
	s_add_i32 s3, s4, 0xfffffbc1
	s_waitcnt lgkmcnt(2)
; #define PG8_LAS __attribute__((address_space(3)))
; __device__ __forceinline__ unsigned fkey(float f) { const unsigned u = __float_as_uint(f); return (u & 0x80000000u) ? ~u : (u | 0x80000000u); }
;     ...
;     const int nj = __builtin_amdgcn_readfirstlane((n + 63) >> 6), ng = (nj + 7) >> 3;
;     const PG8_LAS float* pl = sc + lane;
; #pragma unroll
;     for (int j = 0; j < NJ; ++j) { const unsigned k = fkey(pl[j * 64]); v[j] = (lane < n - j * 64) ? k : 0u; }
;     unsigned T = 1u; int need = 1 << 30;
;     if (n > TOPK) {
;         unsigned prefix = 0u; bool exact;
;         if (NG >= 8 && ng > 7) exact = bit_search<(NG >= 8 ? 8 : NG), NJ, BITLO>(v, prefix);
;         else if (NG >= 7 && ng > 6) exact = bit_search<(NG >= 7 ? 7 : NG), NJ, BITLO>(v, prefix);
;         else if (NG >= 6 && ng > 5) exact = bit_search<(NG >= 6 ? 6 : NG), NJ, BITLO>(v, prefix);
;         else if (NG >= 5 && ng > 4) exact = bit_search<(NG >= 5 ? 5 : NG), NJ, BITLO>(v, prefix);
;         else if (NG >= 4 && ng > 3) exact = bit_search<(NG >= 4 ? 4 : NG), NJ, BITLO>(v, prefix);
;         else if (NG >= 3 && ng > 2) exact = bit_search<(NG >= 3 ? 3 : NG), NJ, BITLO>(v, prefix);
;         else if (NG >= 2 && ng > 1) exact = bit_search<(NG >= 2 ? 2 : NG), NJ, BITLO>(v, prefix);
;         else exact = bit_search<1, NJ, BITLO>(v, prefix);
	v_xor_b32_e32 v25, -1, v23
	v_cndmask_b32_e32 v18, v21, v24, vcc
	v_cmp_gt_i32_e32 vcc, s1, v84
	v_xor_b32_e32 v21, -1, v22
	s_add_i32 s1, s4, 0xfffffb81
	v_cndmask_b32_e32 v24, 0, v18, vcc
	v_cmp_gt_i32_e32 vcc, s3, v84
	v_and_b32_e32 v18, 0x7fffffff, v23
	s_add_i32 s3, s4, 0xfffffb41
	v_cndmask_b32_e32 v20, 0, v19, vcc
	v_and_b32_e32 v19, 0x7fffffff, v22
	v_pk_add_f32 v[18:19], v[18:19], 0 neg_lo:[1,1] neg_hi:[1,1]
	v_cmp_gt_i32_e32 vcc, 0, v23
	s_waitcnt lgkmcnt(1)
	v_and_b32_e32 v31, 0x7fffffff, v26
	v_and_b32_e32 v30, 0x7fffffff, v27
	v_cndmask_b32_e32 v18, v18, v25, vcc
	v_cmp_gt_i32_e32 vcc, 0, v22
	v_pk_add_f32 v[30:31], v[30:31], 0 neg_lo:[1,1] neg_hi:[1,1]
	s_waitcnt lgkmcnt(0)
	v_xor_b32_e32 v25, -1, v29
	v_cndmask_b32_e32 v19, v19, v21, vcc
	v_cmp_gt_i32_e32 vcc, s1, v84
	v_xor_b32_e32 v21, -1, v27
	s_add_i32 s1, s4, 0xfffffb01
	v_cndmask_b32_e32 v23, 0, v19, vcc
	v_cmp_gt_i32_e32 vcc, s3, v84
	s_add_i32 s3, s4, 0xfffffac1
	s_nop 0
	v_cndmask_b32_e32 v19, 0, v18, vcc
	v_cmp_gt_i32_e32 vcc, 0, v27
	v_xor_b32_e32 v18, -1, v26
	v_and_b32_e32 v27, 0x7fffffff, v28
	v_cndmask_b32_e32 v21, v30, v21, vcc
	v_cmp_gt_i32_e32 vcc, 0, v26
	v_and_b32_e32 v26, 0x7fffffff, v29
	v_pk_add_f32 v[26:27], v[26:27], 0 neg_lo:[1,1] neg_hi:[1,1]
	v_cndmask_b32_e32 v18, v31, v18, vcc
	v_cmp_gt_i32_e32 vcc, s1, v84
	s_add_i32 s1, s4, 0xfffffa81
	s_nop 0
	v_cndmask_b32_e32 v22, 0, v18, vcc
	v_cmp_gt_i32_e32 vcc, s3, v84
	s_add_i32 s3, s4, 0xfffffa41
	s_nop 0
	v_cndmask_b32_e32 v18, 0, v21, vcc
	v_cmp_gt_i32_e32 vcc, 0, v29
	v_xor_b32_e32 v21, -1, v28
	s_nop 0
	v_cndmask_b32_e32 v29, v26, v25, vcc
	v_cmp_gt_i32_e32 vcc, 0, v28
	s_nop 1
	v_cndmask_b32_e32 v21, v27, v21, vcc
	ds_read2st64_b32 v[26:27], v58 offset0:24 offset1:25
	v_cmp_gt_i32_e32 vcc, s1, v84
	ds_read2st64_b32 v[30:31], v58 offset0:26 offset1:27
	ds_read2st64_b32 v[34:35], v58 offset0:28 offset1:29
	ds_read2st64_b32 v[36:37], v58 offset0:30 offset1:31
	v_cndmask_b32_e32 v25, 0, v21, vcc
	v_cmp_gt_i32_e32 vcc, s3, v84
	s_waitcnt lgkmcnt(3)
	v_and_b32_e32 v28, 0x7fffffff, v27
	v_xor_b32_e32 v33, -1, v27
	v_cndmask_b32_e32 v21, 0, v29, vcc
	v_and_b32_e32 v29, 0x7fffffff, v26
	v_pk_add_f32 v[28:29], v[28:29], 0 neg_lo:[1,1] neg_hi:[1,1]
	v_cmp_gt_i32_e32 vcc, 0, v27
	v_xor_b32_e32 v32, -1, v26
	s_add_i32 s1, s4, 0xfffffa01
	v_cndmask_b32_e32 v27, v28, v33, vcc
	v_cmp_gt_i32_e32 vcc, 0, v26
	s_add_i32 s3, s4, 0xfffff9c1
	s_waitcnt lgkmcnt(2)
	v_xor_b32_e32 v33, -1, v31
	v_cndmask_b32_e32 v26, v29, v32, vcc
	v_cmp_gt_i32_e32 vcc, s1, v84
	v_xor_b32_e32 v29, -1, v30
	s_add_i32 s1, s4, 0xfffff981
	v_cndmask_b32_e32 v32, 0, v26, vcc
	v_cmp_gt_i32_e32 vcc, s3, v84
	v_and_b32_e32 v26, 0x7fffffff, v31
	s_add_i32 s3, s4, 0xfffff941
	v_cndmask_b32_e32 v28, 0, v27, vcc
	v_and_b32_e32 v27, 0x7fffffff, v30
	v_pk_add_f32 v[26:27], v[26:27], 0 neg_lo:[1,1] neg_hi:[1,1]
	v_cmp_gt_i32_e32 vcc, 0, v31
	s_waitcnt lgkmcnt(1)
	v_and_b32_e32 v39, 0x7fffffff, v34
	v_and_b32_e32 v38, 0x7fffffff, v35
	v_cndmask_b32_e32 v26, v26, v33, vcc
	v_cmp_gt_i32_e32 vcc, 0, v30
	v_pk_add_f32 v[38:39], v[38:39], 0 neg_lo:[1,1] neg_hi:[1,1]
	s_waitcnt lgkmcnt(0)
	v_xor_b32_e32 v33, -1, v37
	v_cndmask_b32_e32 v27, v27, v29, vcc
	v_cmp_gt_i32_e32 vcc, s1, v84
	v_xor_b32_e32 v29, -1, v35
	s_add_i32 s1, s4, 0xfffff901
	v_cndmask_b32_e32 v31, 0, v27, vcc
	v_cmp_gt_i32_e32 vcc, s3, v84
	s_add_i32 s3, s4, 0xfffff8c1
	s_nop 0
	v_cndmask_b32_e32 v27, 0, v26, vcc
	v_cmp_gt_i32_e32 vcc, 0, v35
	v_xor_b32_e32 v26, -1, v34
	v_and_b32_e32 v35, 0x7fffffff, v36
	v_cndmask_b32_e32 v29, v38, v29, vcc
	v_cmp_gt_i32_e32 vcc, 0, v34
	v_and_b32_e32 v34, 0x7fffffff, v37
	v_pk_add_f32 v[34:35], v[34:35], 0 neg_lo:[1,1] neg_hi:[1,1]
	v_cndmask_b32_e32 v26, v39, v26, vcc
	v_cmp_gt_i32_e32 vcc, s1, v84
	s_add_i32 s1, s4, 0xfffff881
	s_nop 0
	v_cndmask_b32_e32 v30, 0, v26, vcc
	v_cmp_gt_i32_e32 vcc, s3, v84
	s_add_i32 s3, s4, 0xfffff841
	s_nop 0
	v_cndmask_b32_e32 v26, 0, v29, vcc
	v_cmp_gt_i32_e32 vcc, 0, v37
	v_xor_b32_e32 v29, -1, v36
	s_nop 0
	v_cndmask_b32_e32 v37, v34, v33, vcc
	v_cmp_gt_i32_e32 vcc, 0, v36
	s_nop 1
	v_cndmask_b32_e32 v29, v35, v29, vcc
	ds_read2st64_b32 v[34:35], v58 offset0:32 offset1:33
	v_cmp_gt_i32_e32 vcc, s1, v84
	ds_read2st64_b32 v[38:39], v58 offset0:34 offset1:35
	ds_read2st64_b32 v[42:43], v58 offset0:36 offset1:37
	ds_read2st64_b32 v[44:45], v58 offset0:38 offset1:39
	v_cndmask_b32_e32 v33, 0, v29, vcc
	v_cmp_gt_i32_e32 vcc, s3, v84
	s_waitcnt lgkmcnt(3)
	v_and_b32_e32 v36, 0x7fffffff, v35
	v_xor_b32_e32 v41, -1, v35
	v_cndmask_b32_e32 v29, 0, v37, vcc
	v_and_b32_e32 v37, 0x7fffffff, v34
	v_pk_add_f32 v[36:37], v[36:37], 0 neg_lo:[1,1] neg_hi:[1,1]
	v_cmp_gt_i32_e32 vcc, 0, v35
	v_xor_b32_e32 v40, -1, v34
	s_add_i32 s1, s4, 0xfffff801
	v_cndmask_b32_e32 v35, v36, v41, vcc
	v_cmp_gt_i32_e32 vcc, 0, v34
	s_add_i32 s3, s4, 0xfffff7c1
	s_waitcnt lgkmcnt(2)
	v_xor_b32_e32 v41, -1, v39
	v_cndmask_b32_e32 v34, v37, v40, vcc
	v_cmp_gt_i32_e32 vcc, s1, v84
	v_xor_b32_e32 v37, -1, v38
	s_add_i32 s1, s4, 0xfffff781
	v_cndmask_b32_e32 v40, 0, v34, vcc
	v_cmp_gt_i32_e32 vcc, s3, v84
	v_and_b32_e32 v34, 0x7fffffff, v39
	s_add_i32 s3, s4, 0xfffff741
	v_cndmask_b32_e32 v36, 0, v35, vcc
	v_and_b32_e32 v35, 0x7fffffff, v38
	v_pk_add_f32 v[34:35], v[34:35], 0 neg_lo:[1,1] neg_hi:[1,1]
	v_cmp_gt_i32_e32 vcc, 0, v39
	s_waitcnt lgkmcnt(1)
	v_and_b32_e32 v47, 0x7fffffff, v42
	v_and_b32_e32 v46, 0x7fffffff, v43
	v_cndmask_b32_e32 v34, v34, v41, vcc
	v_cmp_gt_i32_e32 vcc, 0, v38
	v_pk_add_f32 v[46:47], v[46:47], 0 neg_lo:[1,1] neg_hi:[1,1]
	s_waitcnt lgkmcnt(0)
; #define PG8_LAS __attribute__((address_space(3)))
; __device__ __forceinline__ unsigned fkey(float f) { const unsigned u = __float_as_uint(f); return (u & 0x80000000u) ? ~u : (u | 0x80000000u); }
;     ...
;     const int nj = __builtin_amdgcn_readfirstlane((n + 63) >> 6), ng = (nj + 7) >> 3;
;     const PG8_LAS float* pl = sc + lane;
; #pragma unroll
;     for (int j = 0; j < NJ; ++j) { const unsigned k = fkey(pl[j * 64]); v[j] = (lane < n - j * 64) ? k : 0u; }
;     unsigned T = 1u; int need = 1 << 30;
;     if (n > TOPK) {
;         unsigned prefix = 0u; bool exact;
;         if (NG >= 8 && ng > 7) exact = bit_search<(NG >= 8 ? 8 : NG), NJ, BITLO>(v, prefix);
;         else if (NG >= 7 && ng > 6) exact = bit_search<(NG >= 7 ? 7 : NG), NJ, BITLO>(v, prefix);
;         else if (NG >= 6 && ng > 5) exact = bit_search<(NG >= 6 ? 6 : NG), NJ, BITLO>(v, prefix);
;         else if (NG >= 5 && ng > 4) exact = bit_search<(NG >= 5 ? 5 : NG), NJ, BITLO>(v, prefix);
;         else if (NG >= 4 && ng > 3) exact = bit_search<(NG >= 4 ? 4 : NG), NJ, BITLO>(v, prefix);
;         else if (NG >= 3 && ng > 2) exact = bit_search<(NG >= 3 ? 3 : NG), NJ, BITLO>(v, prefix);
;         else if (NG >= 2 && ng > 1) exact = bit_search<(NG >= 2 ? 2 : NG), NJ, BITLO>(v, prefix);
;         else exact = bit_search<1, NJ, BITLO>(v, prefix);
	v_xor_b32_e32 v41, -1, v45
	v_cndmask_b32_e32 v35, v35, v37, vcc
	v_cmp_gt_i32_e32 vcc, s1, v84
	v_xor_b32_e32 v37, -1, v43
	s_add_i32 s1, s4, 0xfffff701
	v_cndmask_b32_e32 v39, 0, v35, vcc
	v_cmp_gt_i32_e32 vcc, s3, v84
	s_add_i32 s3, s4, 0xfffff6c1
	s_nop 0
	v_cndmask_b32_e32 v35, 0, v34, vcc
	v_cmp_gt_i32_e32 vcc, 0, v43
	v_xor_b32_e32 v34, -1, v42
	v_and_b32_e32 v43, 0x7fffffff, v44
	v_cndmask_b32_e32 v37, v46, v37, vcc
	v_cmp_gt_i32_e32 vcc, 0, v42
	v_and_b32_e32 v42, 0x7fffffff, v45
	v_pk_add_f32 v[42:43], v[42:43], 0 neg_lo:[1,1] neg_hi:[1,1]
	v_cndmask_b32_e32 v34, v47, v34, vcc
	v_cmp_gt_i32_e32 vcc, s1, v84
	s_add_i32 s1, s4, 0xfffff681
	s_nop 0
	v_cndmask_b32_e32 v38, 0, v34, vcc
	v_cmp_gt_i32_e32 vcc, s3, v84
	s_add_i32 s3, s4, 0xfffff641
	s_nop 0
	v_cndmask_b32_e32 v34, 0, v37, vcc
	v_cmp_gt_i32_e32 vcc, 0, v45
	v_xor_b32_e32 v37, -1, v44
	s_nop 0
	v_cndmask_b32_e32 v45, v42, v41, vcc
	v_cmp_gt_i32_e32 vcc, 0, v44
	s_nop 1
	v_cndmask_b32_e32 v37, v43, v37, vcc
	ds_read2st64_b32 v[42:43], v58 offset0:40 offset1:41
	v_cmp_gt_i32_e32 vcc, s1, v84
	ds_read2st64_b32 v[46:47], v58 offset0:42 offset1:43
	ds_read2st64_b32 v[50:51], v58 offset0:44 offset1:45
	ds_read2st64_b32 v[52:53], v58 offset0:46 offset1:47
	v_cndmask_b32_e32 v41, 0, v37, vcc
	v_cmp_gt_i32_e32 vcc, s3, v84
	s_waitcnt lgkmcnt(3)
	v_and_b32_e32 v44, 0x7fffffff, v43
	v_xor_b32_e32 v49, -1, v43
	v_cndmask_b32_e32 v37, 0, v45, vcc
	v_and_b32_e32 v45, 0x7fffffff, v42
	v_pk_add_f32 v[44:45], v[44:45], 0 neg_lo:[1,1] neg_hi:[1,1]
	v_cmp_gt_i32_e32 vcc, 0, v43
	v_xor_b32_e32 v48, -1, v42
	s_add_i32 s1, s4, 0xfffff601
	v_cndmask_b32_e32 v43, v44, v49, vcc
	v_cmp_gt_i32_e32 vcc, 0, v42
	s_add_i32 s3, s4, 0xfffff5c1
	s_waitcnt lgkmcnt(2)
	v_xor_b32_e32 v49, -1, v47
	v_cndmask_b32_e32 v42, v45, v48, vcc
	v_cmp_gt_i32_e32 vcc, s1, v84
	v_xor_b32_e32 v45, -1, v46
	s_add_i32 s1, s4, 0xfffff581
	v_cndmask_b32_e32 v48, 0, v42, vcc
	v_cmp_gt_i32_e32 vcc, s3, v84
	v_and_b32_e32 v42, 0x7fffffff, v47
	s_add_i32 s3, s4, 0xfffff541
	v_cndmask_b32_e32 v44, 0, v43, vcc
	v_and_b32_e32 v43, 0x7fffffff, v46
	v_pk_add_f32 v[42:43], v[42:43], 0 neg_lo:[1,1] neg_hi:[1,1]
	v_cmp_gt_i32_e32 vcc, 0, v47
	s_waitcnt lgkmcnt(1)
	v_and_b32_e32 v55, 0x7fffffff, v50
	v_and_b32_e32 v54, 0x7fffffff, v51
	v_cndmask_b32_e32 v42, v42, v49, vcc
	v_cmp_gt_i32_e32 vcc, 0, v46
	v_pk_add_f32 v[54:55], v[54:55], 0 neg_lo:[1,1] neg_hi:[1,1]
	s_waitcnt lgkmcnt(0)
	v_xor_b32_e32 v49, -1, v53
	v_cndmask_b32_e32 v43, v43, v45, vcc
	v_cmp_gt_i32_e32 vcc, s1, v84
	v_xor_b32_e32 v45, -1, v51
	s_add_i32 s1, s4, 0xfffff501
	v_cndmask_b32_e32 v47, 0, v43, vcc
	v_cmp_gt_i32_e32 vcc, s3, v84
	s_add_i32 s3, s4, 0xfffff4c1
	s_nop 0
	v_cndmask_b32_e32 v43, 0, v42, vcc
	v_cmp_gt_i32_e32 vcc, 0, v51
	v_xor_b32_e32 v42, -1, v50
	v_and_b32_e32 v51, 0x7fffffff, v52
	v_cndmask_b32_e32 v45, v54, v45, vcc
	v_cmp_gt_i32_e32 vcc, 0, v50
	v_and_b32_e32 v50, 0x7fffffff, v53
	v_pk_add_f32 v[50:51], v[50:51], 0 neg_lo:[1,1] neg_hi:[1,1]
	v_cndmask_b32_e32 v42, v55, v42, vcc
	v_cmp_gt_i32_e32 vcc, s1, v84
	s_add_i32 s1, s4, 0xfffff481
	s_nop 0
	v_cndmask_b32_e32 v46, 0, v42, vcc
	v_cmp_gt_i32_e32 vcc, s3, v84
	s_add_i32 s3, s4, 0xfffff441
	s_nop 0
	v_cndmask_b32_e32 v42, 0, v45, vcc
	v_cmp_gt_i32_e32 vcc, 0, v53
	v_xor_b32_e32 v45, -1, v52
	s_nop 0
	v_cndmask_b32_e32 v53, v50, v49, vcc
	v_cmp_gt_i32_e32 vcc, 0, v52
	s_nop 1
	v_cndmask_b32_e32 v45, v51, v45, vcc
	ds_read2st64_b32 v[50:51], v58 offset0:48 offset1:49
	v_cmp_gt_i32_e32 vcc, s1, v84
	ds_read2st64_b32 v[54:55], v58 offset0:50 offset1:51
	ds_read2st64_b32 v[60:61], v58 offset0:52 offset1:53
	ds_read2st64_b32 v[62:63], v58 offset0:54 offset1:55
	v_cndmask_b32_e32 v49, 0, v45, vcc
	v_cmp_gt_i32_e32 vcc, s3, v84
	s_waitcnt lgkmcnt(3)
	v_and_b32_e32 v52, 0x7fffffff, v51
	v_xor_b32_e32 v57, -1, v51
	v_cndmask_b32_e32 v45, 0, v53, vcc
	v_and_b32_e32 v53, 0x7fffffff, v50
	v_pk_add_f32 v[52:53], v[52:53], 0 neg_lo:[1,1] neg_hi:[1,1]
	v_cmp_gt_i32_e32 vcc, 0, v51
	v_xor_b32_e32 v56, -1, v50
	s_add_i32 s1, s4, 0xfffff401
	v_cndmask_b32_e32 v51, v52, v57, vcc
	v_cmp_gt_i32_e32 vcc, 0, v50
	s_add_i32 s3, s4, 0xfffff3c1
	s_waitcnt lgkmcnt(2)
	v_xor_b32_e32 v57, -1, v55
	v_cndmask_b32_e32 v50, v53, v56, vcc
	v_cmp_gt_i32_e32 vcc, s1, v84
	v_xor_b32_e32 v53, -1, v54
	s_add_i32 s1, s4, 0xfffff381
	v_cndmask_b32_e32 v56, 0, v50, vcc
	v_cmp_gt_i32_e32 vcc, s3, v84
	v_and_b32_e32 v50, 0x7fffffff, v55
	s_add_i32 s3, s4, 0xfffff341
	v_cndmask_b32_e32 v52, 0, v51, vcc
	v_and_b32_e32 v51, 0x7fffffff, v54
	v_pk_add_f32 v[50:51], v[50:51], 0 neg_lo:[1,1] neg_hi:[1,1]
	v_cmp_gt_i32_e32 vcc, 0, v55
	s_waitcnt lgkmcnt(1)
; #define PG8_LAS __attribute__((address_space(3)))
; __device__ __forceinline__ unsigned fkey(float f) { const unsigned u = __float_as_uint(f); return (u & 0x80000000u) ? ~u : (u | 0x80000000u); }
;     ...
;     const int nj = __builtin_amdgcn_readfirstlane((n + 63) >> 6), ng = (nj + 7) >> 3;
;     const PG8_LAS float* pl = sc + lane;
; #pragma unroll
;     for (int j = 0; j < NJ; ++j) { const unsigned k = fkey(pl[j * 64]); v[j] = (lane < n - j * 64) ? k : 0u; }
;     unsigned T = 1u; int need = 1 << 30;
;     if (n > TOPK) {
;         unsigned prefix = 0u; bool exact;
;         if (NG >= 8 && ng > 7) exact = bit_search<(NG >= 8 ? 8 : NG), NJ, BITLO>(v, prefix);
;         else if (NG >= 7 && ng > 6) exact = bit_search<(NG >= 7 ? 7 : NG), NJ, BITLO>(v, prefix);
;         else if (NG >= 6 && ng > 5) exact = bit_search<(NG >= 6 ? 6 : NG), NJ, BITLO>(v, prefix);
;         else if (NG >= 5 && ng > 4) exact = bit_search<(NG >= 5 ? 5 : NG), NJ, BITLO>(v, prefix);
;         else if (NG >= 4 && ng > 3) exact = bit_search<(NG >= 4 ? 4 : NG), NJ, BITLO>(v, prefix);
;         else if (NG >= 3 && ng > 2) exact = bit_search<(NG >= 3 ? 3 : NG), NJ, BITLO>(v, prefix);
;         else if (NG >= 2 && ng > 1) exact = bit_search<(NG >= 2 ? 2 : NG), NJ, BITLO>(v, prefix);
;         else exact = bit_search<1, NJ, BITLO>(v, prefix);
	v_and_b32_e32 v65, 0x7fffffff, v60
	v_and_b32_e32 v64, 0x7fffffff, v61
	v_cndmask_b32_e32 v50, v50, v57, vcc
	v_cmp_gt_i32_e32 vcc, 0, v54
	v_pk_add_f32 v[64:65], v[64:65], 0 neg_lo:[1,1] neg_hi:[1,1]
	s_waitcnt lgkmcnt(0)
	v_xor_b32_e32 v57, -1, v63
	v_cndmask_b32_e32 v51, v51, v53, vcc
	v_cmp_gt_i32_e32 vcc, s1, v84
	v_xor_b32_e32 v53, -1, v61
	s_add_i32 s1, s4, 0xfffff301
	v_cndmask_b32_e32 v55, 0, v51, vcc
	v_cmp_gt_i32_e32 vcc, s3, v84
	s_add_i32 s3, s4, 0xfffff2c1
	s_nop 0
	v_cndmask_b32_e32 v51, 0, v50, vcc
	v_cmp_gt_i32_e32 vcc, 0, v61
	v_xor_b32_e32 v50, -1, v60
	v_and_b32_e32 v61, 0x7fffffff, v62
	v_cndmask_b32_e32 v53, v64, v53, vcc
	v_cmp_gt_i32_e32 vcc, 0, v60
	v_and_b32_e32 v60, 0x7fffffff, v63
	v_pk_add_f32 v[60:61], v[60:61], 0 neg_lo:[1,1] neg_hi:[1,1]
	v_cndmask_b32_e32 v50, v65, v50, vcc
	v_cmp_gt_i32_e32 vcc, s1, v84
	s_add_i32 s1, s4, 0xfffff281
	s_nop 0
	v_cndmask_b32_e32 v54, 0, v50, vcc
	v_cmp_gt_i32_e32 vcc, s3, v84
	s_add_i32 s3, s4, 0xfffff241
	s_nop 0
	v_cndmask_b32_e32 v50, 0, v53, vcc
	v_cmp_gt_i32_e32 vcc, 0, v63
	v_xor_b32_e32 v53, -1, v62
	s_nop 0
	v_cndmask_b32_e32 v59, v60, v57, vcc
	v_cmp_gt_i32_e32 vcc, 0, v62
	s_nop 1
	v_cndmask_b32_e32 v53, v61, v53, vcc
	ds_read2st64_b32 v[60:61], v58 offset0:56 offset1:57
	v_cmp_gt_i32_e32 vcc, s1, v84
	ds_read2st64_b32 v[62:63], v58 offset0:58 offset1:59
	ds_read2st64_b32 v[66:67], v58 offset0:60 offset1:61
	ds_read2st64_b32 v[68:69], v58 offset0:62 offset1:63
	v_cndmask_b32_e32 v57, 0, v53, vcc
	v_cmp_gt_i32_e32 vcc, s3, v84
	s_waitcnt lgkmcnt(3)
	v_and_b32_e32 v58, 0x7fffffff, v61
	v_xor_b32_e32 v65, -1, v61
	v_cndmask_b32_e32 v53, 0, v59, vcc
	v_and_b32_e32 v59, 0x7fffffff, v60
	v_pk_add_f32 v[58:59], v[58:59], 0 neg_lo:[1,1] neg_hi:[1,1]
	v_cmp_gt_i32_e32 vcc, 0, v61
	v_xor_b32_e32 v64, -1, v60
	s_add_i32 s1, s4, 0xfffff201
	v_cndmask_b32_e32 v58, v58, v65, vcc
	v_cmp_gt_i32_e32 vcc, 0, v60
	s_add_i32 s3, s4, 0xfffff1c1
	s_waitcnt lgkmcnt(2)
	v_xor_b32_e32 v65, -1, v63
	v_cndmask_b32_e32 v59, v59, v64, vcc
	v_cmp_gt_i32_e32 vcc, s1, v84
	v_xor_b32_e32 v61, -1, v62
	s_add_i32 s1, s4, 0xfffff181
	v_cndmask_b32_e32 v64, 0, v59, vcc
	v_cmp_gt_i32_e32 vcc, s3, v84
	v_and_b32_e32 v59, 0x7fffffff, v62
	s_add_i32 s3, s4, 0xfffff141
	v_cndmask_b32_e32 v60, 0, v58, vcc
	v_and_b32_e32 v58, 0x7fffffff, v63
	v_pk_add_f32 v[58:59], v[58:59], 0 neg_lo:[1,1] neg_hi:[1,1]
	v_cmp_gt_i32_e32 vcc, 0, v63
	s_waitcnt lgkmcnt(1)
	v_and_b32_e32 v71, 0x7fffffff, v66
	v_and_b32_e32 v70, 0x7fffffff, v67
	v_cndmask_b32_e32 v58, v58, v65, vcc
	v_cmp_gt_i32_e32 vcc, 0, v62
	v_pk_add_f32 v[70:71], v[70:71], 0 neg_lo:[1,1] neg_hi:[1,1]
	s_waitcnt lgkmcnt(0)
	v_xor_b32_e32 v65, -1, v69
	v_cndmask_b32_e32 v59, v59, v61, vcc
	v_cmp_gt_i32_e32 vcc, s1, v84
	v_xor_b32_e32 v61, -1, v67
	s_add_i32 s1, s4, 0xfffff101
	v_cndmask_b32_e32 v63, 0, v59, vcc
	v_cmp_gt_i32_e32 vcc, s3, v84
	s_add_i32 s3, s4, 0xfffff0c1
	s_nop 0
	v_cndmask_b32_e32 v59, 0, v58, vcc
	v_cmp_gt_i32_e32 vcc, 0, v67
	v_xor_b32_e32 v58, -1, v66
	v_and_b32_e32 v67, 0x7fffffff, v68
	v_cndmask_b32_e32 v62, v70, v61, vcc
	v_cmp_gt_i32_e32 vcc, 0, v66
	v_and_b32_e32 v66, 0x7fffffff, v69
	v_pk_add_f32 v[66:67], v[66:67], 0 neg_lo:[1,1] neg_hi:[1,1]
	v_cndmask_b32_e32 v58, v71, v58, vcc
	v_cmp_gt_i32_e32 vcc, s1, v84
	s_add_i32 s1, s4, 0xfffff081
	s_nop 0
	v_cndmask_b32_e32 v61, 0, v58, vcc
	v_cmp_gt_i32_e32 vcc, s3, v84
	s_add_i32 s3, s4, 0xfffff041
	s_cmpk_lt_i32 s4, 0x100
	v_cndmask_b32_e32 v58, 0, v62, vcc
	v_cmp_gt_i32_e32 vcc, 0, v69
	v_xor_b32_e32 v62, -1, v68
	s_nop 0
	v_cndmask_b32_e32 v66, v66, v65, vcc
	v_cmp_gt_i32_e32 vcc, 0, v68
	s_nop 1
	v_cndmask_b32_e32 v62, v67, v62, vcc
	v_cmp_gt_i32_e32 vcc, s1, v84
	s_nop 1
	v_cndmask_b32_e32 v65, 0, v62, vcc
	v_cmp_gt_i32_e32 vcc, s3, v84
	s_nop 1
	v_cndmask_b32_e32 v62, 0, v66, vcc
	s_cbranch_scc1 .LBB0_1228
	s_cmp_gt_i32 s10, 7
	s_cselect_b64 s[0:1], -1, 0
	s_cmp_lt_i32 s10, 8
	s_cbranch_scc0 .LBB0_1229
	s_cmp_lg_u32 s10, 7
	s_cbranch_scc0 .LBB0_1231
	s_cmp_lt_i32 s10, 6
	s_cbranch_scc0 .LBB0_1233
	s_cmp_lg_u32 s10, 5
	s_cbranch_scc0 .LBB0_1234
	s_cmp_lt_i32 s10, 4
	s_cbranch_scc0 .LBB0_1235
	s_cmp_lg_u32 s10, 3
	s_cbranch_scc0 .LBB0_1236
	s_cmp_gt_i32 s10, 1
	s_cbranch_scc1 .LBB0_1237
	v_mov_b32_e32 v67, 31
	v_mov_b32_e32 v66, 0

; __device__ __forceinline__ void idx_load_q(IdxQ& q, const bf16_t* QI, const float* WI, int grow0, int lane) {
;     static_assert(IDX_SPLIT == 1, "q_idx is stored in bf16");
;     const int rho = lane & 31, kh = lane >> 5, ql = 2 * ((rho >> 2) & 1) + (rho >> 4), head = 4 * ((rho >> 3) & 1) + (rho & 3);
;     const bf16_t* src = QI + (size_t)(grow0 + ql) * 512 + head * IDD + kh * 8;
; #pragma unroll
;     for (int ks = 0; ks < 4; ++ks) { q.hi[ks] = *(const bf16x8*)(src + ks * 16); q.lo[ks] = q.hi[ks]; }
; #pragma unroll
;     for (int e = 0; e < 2; ++e) {
;         const float* wsrc = WI + (size_t)(grow0 + 2 * kh + e) * 8;
;         const f32x4 a = *(const f32x4*)wsrc, b = *(const f32x4*)(wsrc + 4);
; #pragma unroll
;         for (int i = 0; i < 4; ++i) { q.w[e * 8 + i] = a[i] * IDX_W_SCALE; q.w[e * 8 + 4 + i] = b[i] * IDX_W_SCALE; }
;     }
; }
; __device__ __forceinline__ void idx_load_raw(IdxRaw& raw, const float* kp) {
; #pragma unroll
;     for (int ks = 0; ks < 4; ++ks) { raw.v[2 * ks] = *(const f32x4*)(kp + ks * 16); raw.v[2 * ks + 1] = *(const f32x4*)(kp + ks * 16 + 4); }
; __device__ __forceinline__ void idx_sample_batch_unit(const Params& p, PG8_LAS unsigned char* lds, int bs) {
;     ...
;     IdxQ q; idx_load_q(q, QI, WI, MP + bs * DS, lane);
;     IdxRaw raw; IdxKey k;
;     for (int pg = wave; pg < NPAGES; pg += NWAVES) {
;         const int phys = page_table[bs * NPAGES + pg];
;         const float* pbase = cache_ki + (size_t)phys * PAGE * IDD + (size_t)r * IDD + kh * 8;
;         idx_load_raw(raw, pbase);
; #pragma unroll
;         for (int tt = 0; tt < 4; ++tt) {
;             idx_cvt_key(raw, k);
;             if (tt < 3) idx_load_raw(raw, pbase + (size_t)(tt + 1) * 32 * IDD);
.LBB0_1691:
	s_andn2_b64 vcc, exec, s[0:1]
	s_cbranch_vccnz .LBB0_865
	v_mov_b32_e32 v42, v0
	s_lshl_b32 s23, s40, 2
	v_bfe_u32 v2, v42, 1, 5
	s_or_b32 s5, s23, 0x2000
	v_and_b32_e32 v3, 2, v2
	v_bfe_u32 v4, v42, 4, 1
	v_and_b32_e32 v53, 3, v42
	v_and_or_b32 v5, v2, 4, v53
	v_or3_b32 v2, v4, v3, s5
	v_lshlrev_b32_e32 v98, 10, v2
	v_bfe_u32 v44, v42, 5, 1
	v_lshl_add_u64 v[2:3], s[64:65], 0, v[98:99]
	v_lshlrev_b32_e32 v98, 7, v5
	v_lshl_add_u64 v[2:3], v[2:3], 0, v[98:99]
	v_lshlrev_b32_e32 v98, 4, v44
	v_lshl_add_u64 v[2:3], v[2:3], 0, v[98:99]
	v_lshl_or_b32 v98, s5, 3, v98
	global_load_dwordx4 v[30:33], v[2:3], off
	global_load_dwordx4 v[26:29], v[2:3], off offset:32
	global_load_dwordx4 v[22:25], v[2:3], off offset:64
	global_load_dwordx4 v[18:21], v[2:3], off offset:96
	v_lshl_add_u64 v[14:15], v[98:99], 2, s[66:67]
	global_load_dwordx4 v[2:5], v[14:15], off offset:48
	global_load_dwordx4 v[6:9], v[14:15], off offset:32
	global_load_dwordx4 v[10:13], v[14:15], off offset:16
	s_nop 0
	global_load_dwordx4 v[14:17], v[14:15], off
	v_readfirstlane_b32 s4, v42
	s_ashr_i32 s80, s4, 6
	v_and_b32_e32 v43, 31, v42
	v_lshlrev_b32_e32 v58, 3, v44
	s_cmp_gt_i32 s80, 63
	s_waitcnt vmcnt(3)
	v_mul_f32_e32 v57, 0x3eb504f3, v2
	s_waitcnt vmcnt(2)
	v_mul_f32_e32 v62, 0x3eb504f3, v6
	s_waitcnt vmcnt(1)
	v_mul_f32_e32 v48, 0x3eb504f3, v10
	s_waitcnt vmcnt(0)
	v_mul_f32_e32 v52, 0x3eb504f3, v14
	v_mul_f32_e32 v51, 0x3eb504f3, v15
	v_mul_f32_e32 v47, 0x3eb504f3, v11
	v_mul_f32_e32 v50, 0x3eb504f3, v16
	v_mul_f32_e32 v46, 0x3eb504f3, v12
	v_mul_f32_e32 v49, 0x3eb504f3, v17
	v_mul_f32_e32 v45, 0x3eb504f3, v13
	v_mul_f32_e32 v61, 0x3eb504f3, v7
	v_mul_f32_e32 v56, 0x3eb504f3, v3
	v_mul_f32_e32 v60, 0x3eb504f3, v8
	v_mul_f32_e32 v55, 0x3eb504f3, v4
	v_mul_f32_e32 v59, 0x3eb504f3, v9
	v_mul_f32_e32 v54, 0x3eb504f3, v5
	s_cbranch_scc1 .LBB0_1695
	s_lshl_b32 s0, s40, 6
	v_readlane_b32 s36, v239, 2
	v_lshlrev_b32_e32 v98, 8, v43
	v_readlane_b32 s44, v239, 10
	v_readlane_b32 s45, v239, 11
	s_lshl_b32 s1, s80, 9
	s_add_i32 s0, s80, s0
	v_lshl_add_u64 v[2:3], s[44:45], 0, v[98:99]
	v_lshlrev_b32_e32 v98, 2, v58
	v_lshl_add_u64 v[38:39], v[2:3], 0, v[98:99]
	v_mov_b32_e32 v2, s1
	s_mov_b32 s1, 0x10040
	v_mad_u32_u24 v2, v44, s1, v2
	s_ashr_i32 s1, s0, 31
	v_readlane_b32 s50, v239, 16
	s_add_i32 s6, s80, -8
	s_lshl_b64 s[0:1], s[0:1], 2
	v_readlane_b32 s51, v239, 17
	v_lshlrev_b32_e32 v3, 2, v43
	s_add_u32 s0, s50, s0
	v_add3_u32 v63, v2, v3, 0
	s_addc_u32 s1, s51, s1
	v_readlane_b32 s37, v239, 3
	v_readlane_b32 s38, v239, 4
	v_readlane_b32 s39, v239, 5
	v_readlane_b32 s40, v239, 6
	v_readlane_b32 s41, v239, 7
	v_readlane_b32 s42, v239, 8
	v_readlane_b32 s43, v239, 9
	v_readlane_b32 s46, v239, 12
	v_readlane_b32 s47, v239, 13
	v_readlane_b32 s48, v239, 14
	v_readlane_b32 s49, v239, 15
	v_and_b32_e32 v115, 7, v42
	v_lshlrev_b32_e32 v115, 5, v115
	global_load_dword v114, v115, s[0:1]
	v_lshlrev_b32_e32 v115, 8, v43
	v_lshl_add_u32 v115, v58, 2, v115
	s_waitcnt vmcnt(0)
	v_readlane_b32 s5, v114, 0
	v_mov_b32_e32 v116, s5
	v_lshl_add_u32 v116, v116, 15, v115
	global_load_dwordx4 v[120:123], v116, s[44:45]
	global_load_dwordx4 v[124:127], v116, s[44:45] offset:16
	global_load_dwordx4 v[128:131], v116, s[44:45] offset:64
	global_load_dwordx4 v[132:135], v116, s[44:45] offset:80
	global_load_dwordx4 v[136:139], v116, s[44:45] offset:128
	global_load_dwordx4 v[140:143], v116, s[44:45] offset:144
	global_load_dwordx4 v[144:147], v116, s[44:45] offset:192
	global_load_dwordx4 v[148:151], v116, s[44:45] offset:208
	v_add_u32_e32 v118, 0x2000, v116
	global_load_dwordx4 v[158:161], v118, s[44:45]
	global_load_dwordx4 v[162:165], v118, s[44:45] offset:16
	global_load_dwordx4 v[166:169], v118, s[44:45] offset:64
	global_load_dwordx4 v[170:173], v118, s[44:45] offset:80
	global_load_dwordx4 v[174:177], v118, s[44:45] offset:128
	global_load_dwordx4 v[178:181], v118, s[44:45] offset:144
	global_load_dwordx4 v[182:185], v118, s[44:45] offset:192
	global_load_dwordx4 v[186:189], v118, s[44:45] offset:208
	v_add_u32_e32 v118, 0x4000, v116
	global_load_dwordx4 v[190:193], v118, s[44:45]
	global_load_dwordx4 v[194:197], v118, s[44:45] offset:16
	global_load_dwordx4 v[198:201], v118, s[44:45] offset:64
	global_load_dwordx4 v[202:205], v118, s[44:45] offset:80
	global_load_dwordx4 v[206:209], v118, s[44:45] offset:128
	global_load_dwordx4 v[210:213], v118, s[44:45] offset:144
	global_load_dwordx4 v[214:217], v118, s[44:45] offset:192
	global_load_dwordx4 v[218:221], v118, s[44:45] offset:208
	v_add_u32_e32 v118, 0x6000, v116
	global_load_dwordx4 v[222:225], v118, s[44:45]
	global_load_dwordx4 v[226:229], v118, s[44:45] offset:16
	global_load_dwordx4 v[230:233], v118, s[44:45] offset:64
	global_load_dwordx4 v[234:237], v118, s[44:45] offset:80
	global_load_dwordx4 v[240:243], v118, s[44:45] offset:128
	global_load_dwordx4 v[244:247], v118, s[44:45] offset:144
	global_load_dwordx4 v[248:251], v118, s[44:45] offset:192
	global_load_dwordx4 v[252:255], v118, s[44:45] offset:208
.LBB0_1694:
	s_mov_b64 s[8:9], 0x20c0
	s_movk_i32 s3, 0x4000
	s_add_i32 s6, s6, 8
	s_lshr_b32 s7, s6, 3
	s_add_i32 s7, s7, 1
	s_add_u32 s0, s0, 32
	s_addc_u32 s1, s1, 0
	s_cmp_gt_i32 s6, 55
	s_nop 3
	v_readlane_b32 s5, v114, s7
	v_mov_b32_e32 v116, s5
	v_lshl_add_u32 v116, v116, 15, v115
	v_ashrrev_i32_e32 v3, 31, v2
	v_lshlrev_b64 v[2:3], 15, v[2:3]
	v_lshl_add_u64 v[40:41], v[38:39], 0, v[2:3]
	s_cbranch_scc1 .Lsbr_w0_0
	s_waitcnt vmcnt(24)
	s_branch .Lsbr_c_0

; __device__ __forceinline__ void split8(const f32x4 a, const f32x4 b, bf16x8& hi, bf16x8& lo) {
;     u32x4 h; h.x = cvt_pk_bf16(a[0], a[1]); h.y = cvt_pk_bf16(a[2], a[3]); h.z = cvt_pk_bf16(b[0], b[1]); h.w = cvt_pk_bf16(b[2], b[3]);
;     u32x4 l;
;     l.x = cvt_pk_bf16(a[0] - __uint_as_float(h.x << 16), a[1] - __uint_as_float(h.x & 0xffff0000u));
;     l.y = cvt_pk_bf16(a[2] - __uint_as_float(h.y << 16), a[3] - __uint_as_float(h.y & 0xffff0000u));
;     l.z = cvt_pk_bf16(b[0] - __uint_as_float(h.z << 16), b[1] - __uint_as_float(h.z & 0xffff0000u));
;     l.w = cvt_pk_bf16(b[2] - __uint_as_float(h.w << 16), b[3] - __uint_as_float(h.w & 0xffff0000u));
;     hi = __builtin_bit_cast(bf16x8, h); lo = __builtin_bit_cast(bf16x8, l);
; }
; __device__ __forceinline__ void idx_load_q(IdxQ& q, const bf16_t* QI, const float* WI, int grow0, int lane) {
;     static_assert(IDX_SPLIT == 1, "q_idx is stored in bf16");
;     const int rho = lane & 31, kh = lane >> 5, ql = 2 * ((rho >> 2) & 1) + (rho >> 4), head = 4 * ((rho >> 3) & 1) + (rho & 3);
;     const bf16_t* src = QI + (size_t)(grow0 + ql) * 512 + head * IDD + kh * 8;
; #pragma unroll
;     for (int ks = 0; ks < 4; ++ks) { q.hi[ks] = *(const bf16x8*)(src + ks * 16); q.lo[ks] = q.hi[ks]; }
; #pragma unroll
;     for (int e = 0; e < 2; ++e) {
;         const float* wsrc = WI + (size_t)(grow0 + 2 * kh + e) * 8;
;         const f32x4 a = *(const f32x4*)wsrc, b = *(const f32x4*)(wsrc + 4);
; #pragma unroll
;         for (int i = 0; i < 4; ++i) { q.w[e * 8 + i] = a[i] * IDX_W_SCALE; q.w[e * 8 + 4 + i] = b[i] * IDX_W_SCALE; }
;     }
; }
; __device__ __forceinline__ void idx_load_raw(IdxRaw& raw, const float* kp) {
; #pragma unroll
;     for (int ks = 0; ks < 4; ++ks) { raw.v[2 * ks] = *(const f32x4*)(kp + ks * 16); raw.v[2 * ks + 1] = *(const f32x4*)(kp + ks * 16 + 4); }
; }
; __device__ __forceinline__ void idx_cvt_key(const IdxRaw& raw, IdxKey& k) {
; #pragma unroll
;     for (int ks = 0; ks < 4; ++ks) split8(raw.v[2 * ks], raw.v[2 * ks + 1], k.hi[ks], k.lo[ks]);
; }
; __device__ __forceinline__ void idx_sample_batch_unit(const Params& p, PG8_LAS unsigned char* lds, int bs) {
;     ...
; #pragma unroll
;         for (int tt = 0; tt < 4; ++tt) {
;             idx_cvt_key(raw, k);
;             if (tt < 3) idx_load_raw(raw, pbase + (size_t)(tt + 1) * 32 * IDD);
;             float s2[2]; idx_tile(q, k, s2);
.Lsbr_c_0:
	v_mov_b64_e32 v[6:7], v[120:121]
	v_mov_b64_e32 v[8:9], v[122:123]
	v_mov_b64_e32 v[2:3], v[124:125]
	v_mov_b64_e32 v[4:5], v[126:127]
	v_mov_b64_e32 v[14:15], v[128:129]
	v_mov_b64_e32 v[16:17], v[130:131]
	v_mov_b64_e32 v[10:11], v[132:133]
	v_mov_b64_e32 v[12:13], v[134:135]
	v_mov_b64_e32 v[64:65], v[136:137]
	v_mov_b64_e32 v[66:67], v[138:139]
	v_mov_b64_e32 v[34:35], v[140:141]
	v_mov_b64_e32 v[36:37], v[142:143]
	v_mov_b64_e32 v[72:73], v[144:145]
	v_mov_b64_e32 v[74:75], v[146:147]
	v_mov_b64_e32 v[68:69], v[148:149]
	v_mov_b64_e32 v[70:71], v[150:151]
	s_cbranch_scc1 .Lsbr_n_0
	global_load_dwordx4 v[120:123], v116, s[44:45]
	global_load_dwordx4 v[124:127], v116, s[44:45] offset:16
	global_load_dwordx4 v[128:131], v116, s[44:45] offset:64
	global_load_dwordx4 v[132:135], v116, s[44:45] offset:80
	global_load_dwordx4 v[136:139], v116, s[44:45] offset:128
	global_load_dwordx4 v[140:143], v116, s[44:45] offset:144
	global_load_dwordx4 v[144:147], v116, s[44:45] offset:192
	global_load_dwordx4 v[148:151], v116, s[44:45] offset:208
.Lsbr_n_0:
	v_cvt_pk_bf16_f32 v76, v6, v7
	s_nop 0
	v_lshlrev_b32_e32 v80, 16, v76
	v_sub_f32_e32 v6, v6, v80
	v_and_b32_e32 v80, 0xffff0000, v76
	v_cvt_pk_bf16_f32 v77, v8, v9
	v_cvt_pk_bf16_f32 v78, v2, v3
	v_cvt_pk_bf16_f32 v79, v4, v5
	v_sub_f32_e32 v7, v7, v80
	v_cvt_pk_bf16_f32 v6, v6, v7
	v_and_b32_e32 v7, 0xffff0000, v77
	v_lshlrev_b32_e32 v6, 16, v77
	v_sub_f32_e32 v6, v8, v6
	v_sub_f32_e32 v7, v9, v7
	v_cvt_pk_bf16_f32 v6, v6, v7
	s_nop 0
	v_lshlrev_b32_e32 v6, 16, v78
	v_sub_f32_e32 v2, v2, v6
	v_and_b32_e32 v6, 0xffff0000, v78
	v_sub_f32_e32 v3, v3, v6
	v_cvt_pk_bf16_f32 v2, v2, v3
	v_and_b32_e32 v3, 0xffff0000, v79
	v_lshlrev_b32_e32 v2, 16, v79
	v_sub_f32_e32 v2, v4, v2
	v_sub_f32_e32 v3, v5, v3
	v_cvt_pk_bf16_f32 v2, v2, v3
	v_cvt_pk_bf16_f32 v80, v14, v15
	v_cvt_pk_bf16_f32 v81, v16, v17
	v_cvt_pk_bf16_f32 v82, v10, v11
	v_cvt_pk_bf16_f32 v83, v12, v13
	v_add_co_u32_e32 v4, vcc, s17, v40
	v_lshlrev_b32_e32 v2, 16, v80
	v_sub_f32_e32 v2, v14, v2
	v_and_b32_e32 v3, 0xffff0000, v80
	v_sub_f32_e32 v3, v15, v3
	v_cvt_pk_bf16_f32 v2, v2, v3
	v_and_b32_e32 v3, 0xffff0000, v81
	v_lshlrev_b32_e32 v2, 16, v81
	v_sub_f32_e32 v2, v16, v2
	v_sub_f32_e32 v3, v17, v3
	v_cvt_pk_bf16_f32 v2, v2, v3
	v_and_b32_e32 v3, 0xffff0000, v82
	v_lshlrev_b32_e32 v2, 16, v82
	v_sub_f32_e32 v2, v10, v2
	v_sub_f32_e32 v3, v11, v3
	v_cvt_pk_bf16_f32 v2, v2, v3
	v_and_b32_e32 v3, 0xffff0000, v83
	v_lshlrev_b32_e32 v2, 16, v83
	v_sub_f32_e32 v2, v12, v2
	v_sub_f32_e32 v3, v13, v3
	v_cvt_pk_bf16_f32 v2, v2, v3
	v_cvt_pk_bf16_f32 v84, v64, v65
	v_cvt_pk_bf16_f32 v85, v66, v67
	v_cvt_pk_bf16_f32 v86, v34, v35
	v_cvt_pk_bf16_f32 v87, v36, v37
	v_addc_co_u32_e32 v5, vcc, 0, v41, vcc
	v_lshlrev_b32_e32 v2, 16, v84
	v_sub_f32_e32 v2, v64, v2
	v_and_b32_e32 v3, 0xffff0000, v84
	v_sub_f32_e32 v3, v65, v3
	v_cvt_pk_bf16_f32 v2, v2, v3
	v_and_b32_e32 v3, 0xffff0000, v85
	v_lshlrev_b32_e32 v2, 16, v85
	v_sub_f32_e32 v2, v66, v2
	v_sub_f32_e32 v3, v67, v3
	v_cvt_pk_bf16_f32 v2, v2, v3
	v_and_b32_e32 v3, 0xffff0000, v86
	v_lshlrev_b32_e32 v2, 16, v86
	v_sub_f32_e32 v2, v34, v2
	v_sub_f32_e32 v3, v35, v3
	v_cvt_pk_bf16_f32 v2, v2, v3
	v_and_b32_e32 v3, 0xffff0000, v87
	v_lshlrev_b32_e32 v2, 16, v87
	v_sub_f32_e32 v2, v36, v2
	v_sub_f32_e32 v3, v37, v3
	v_cvt_pk_bf16_f32 v2, v2, v3
	v_cvt_pk_bf16_f32 v34, v72, v73
	v_cvt_pk_bf16_f32 v35, v74, v75
	v_cvt_pk_bf16_f32 v36, v68, v69
	v_cvt_pk_bf16_f32 v37, v70, v71
	s_nop 0
	v_lshlrev_b32_e32 v2, 16, v34
	v_sub_f32_e32 v2, v72, v2
	v_and_b32_e32 v3, 0xffff0000, v34
	v_sub_f32_e32 v3, v73, v3
	v_cvt_pk_bf16_f32 v2, v2, v3
	v_and_b32_e32 v3, 0xffff0000, v35
	v_lshlrev_b32_e32 v2, 16, v35
	v_sub_f32_e32 v2, v74, v2
	v_sub_f32_e32 v3, v75, v3
	v_cvt_pk_bf16_f32 v2, v2, v3
	v_and_b32_e32 v3, 0xffff0000, v36
	v_lshlrev_b32_e32 v2, 16, v36
	v_sub_f32_e32 v2, v68, v2
	v_sub_f32_e32 v3, v69, v3
	v_cvt_pk_bf16_f32 v2, v2, v3
	v_and_b32_e32 v3, 0xffff0000, v37
	v_lshlrev_b32_e32 v2, 16, v37
	v_sub_f32_e32 v2, v70, v2
	v_sub_f32_e32 v3, v71, v3
	v_cvt_pk_bf16_f32 v2, v2, v3
	s_nop 0
	v_lshl_add_u64 v[2:3], v[40:41], 0, s[8:9]
	s_mov_b64 s[8:9], 0x2080
	s_cbranch_scc1 .Lsbr_w0_1
	s_waitcnt vmcnt(24)
	s_branch .Lsbr_c_1

; __device__ __forceinline__ void idx_tile(const IdxQ& q, const IdxKey& k, float (&s)[2]) {
;     f32x16 acc;
; #pragma unroll
;     for (int i = 0; i < 16; ++i) acc[i] = 0.f;
; #pragma unroll
;     for (int ks = 0; ks < 4; ++ks) {
;         acc = __builtin_amdgcn_mfma_f32_32x32x16_bf16(q.hi[ks], k.hi[ks], acc, 0, 0, 0);
;         if (IDX_SPLIT == 3) { acc = __builtin_amdgcn_mfma_f32_32x32x16_bf16(q.hi[ks], k.lo[ks], acc, 0, 0, 0); acc = __builtin_amdgcn_mfma_f32_32x32x16_bf16(q.lo[ks], k.hi[ks], acc, 0, 0, 0); }
;     }
; #pragma unroll
;     for (int e = 0; e < 2; ++e) {
;         float t = 0.f;
; #pragma unroll
;         for (int i = 0; i < 8; ++i) t += fmaxf(acc[e * 8 + i] * IDX_SCALE, 0.f) * q.w[e * 8 + i];
;         s[e] = t;
;     }
; __device__ __forceinline__ void idx_sample_batch_unit(const Params& p, PG8_LAS unsigned char* lds, int bs) {
;     ...
;         for (int tt = 0; tt < 4; ++tt) {
;             idx_cvt_key(raw, k);
;             if (tt < 3) idx_load_raw(raw, pbase + (size_t)(tt + 1) * 32 * IDD);
;             float s2[2]; idx_tile(q, k, s2);
;             const int col = pg * PAGE + tt * 32 + r;
;             sc[(2 * kh) * SCS_LDL + col] = s2[0]; sc[(2 * kh + 1) * SCS_LDL + col] = s2[1];
.Lsbr_c_1:
	v_mov_b64_e32 v[106:107], v[158:159]
	v_mov_b64_e32 v[108:109], v[160:161]
	v_mov_b64_e32 v[110:111], v[162:163]
	v_mov_b64_e32 v[112:113], v[164:165]
	v_mov_b64_e32 v[92:93], v[166:167]
	v_mov_b64_e32 v[94:95], v[168:169]
	v_mov_b64_e32 v[102:103], v[170:171]
	v_mov_b64_e32 v[104:105], v[172:173]
	v_mov_b64_e32 v[72:73], v[174:175]
	v_mov_b64_e32 v[74:75], v[176:177]
	v_mov_b64_e32 v[88:89], v[178:179]
	v_mov_b64_e32 v[90:91], v[180:181]
	v_mov_b64_e32 v[64:65], v[182:183]
	v_mov_b64_e32 v[66:67], v[184:185]
	v_mov_b64_e32 v[68:69], v[186:187]
	v_mov_b64_e32 v[70:71], v[188:189]
	s_cbranch_scc1 .Lsbr_n_1
	v_add_u32_e32 v118, 0x2000, v116
	global_load_dwordx4 v[158:161], v118, s[44:45]
	global_load_dwordx4 v[162:165], v118, s[44:45] offset:16
	global_load_dwordx4 v[166:169], v118, s[44:45] offset:64
	global_load_dwordx4 v[170:173], v118, s[44:45] offset:80
	global_load_dwordx4 v[174:177], v118, s[44:45] offset:128
	global_load_dwordx4 v[178:181], v118, s[44:45] offset:144
	global_load_dwordx4 v[182:185], v118, s[44:45] offset:192
	global_load_dwordx4 v[186:189], v118, s[44:45] offset:208
.Lsbr_n_1:
	v_lshl_add_u64 v[2:3], v[40:41], 0, s[8:9]
	s_mov_b64 s[8:9], 0x2040
	v_lshl_add_u64 v[2:3], v[40:41], 0, s[8:9]
	v_lshl_add_u64 v[2:3], v[40:41], 0, s[96:97]
	v_mfma_f32_32x32x16_bf16 v[2:17], v[30:33], v[76:79], 0
	s_mov_b64 s[8:9], 0x40c0
	v_mfma_f32_32x32x16_bf16 v[2:17], v[26:29], v[80:83], v[2:17]
	v_mfma_f32_32x32x16_bf16 v[2:17], v[22:25], v[84:87], v[2:17]
	v_mfma_f32_32x32x16_bf16 v[2:17], v[18:21], v[34:37], v[2:17]
	s_nop 11
	v_mul_f32_e32 v2, 0x3e000000, v2
	v_max_f32_e32 v2, 0, v2
	v_mul_f32_e32 v3, 0x3e000000, v3
	v_fma_f32 v2, v52, v2, 0
	v_max_f32_e32 v3, 0, v3
	v_fmac_f32_e32 v2, v51, v3
	v_mul_f32_e32 v3, 0x3e000000, v4
	v_max_f32_e32 v3, 0, v3
	v_fmac_f32_e32 v2, v50, v3
	v_mul_f32_e32 v3, 0x3e000000, v5
	v_max_f32_e32 v3, 0, v3
	v_fmac_f32_e32 v2, v49, v3
	v_mul_f32_e32 v3, 0x3e000000, v6
	v_max_f32_e32 v3, 0, v3
	v_fmac_f32_e32 v2, v48, v3
	v_mul_f32_e32 v3, 0x3e000000, v7
	v_max_f32_e32 v3, 0, v3
	v_fmac_f32_e32 v2, v47, v3
	v_mul_f32_e32 v3, 0x3e000000, v8
	v_max_f32_e32 v3, 0, v3
	v_fmac_f32_e32 v2, v46, v3
	v_mul_f32_e32 v3, 0x3e000000, v9
	v_max_f32_e32 v3, 0, v3
	v_fmac_f32_e32 v2, v45, v3
	v_mul_f32_e32 v3, 0x3e000000, v10
	v_max_f32_e32 v3, 0, v3
	v_mul_f32_e32 v4, 0x3e000000, v11
	v_fma_f32 v3, v62, v3, 0
	v_max_f32_e32 v4, 0, v4
	v_fmac_f32_e32 v3, v61, v4
	v_mul_f32_e32 v4, 0x3e000000, v12
	v_max_f32_e32 v4, 0, v4
	v_fmac_f32_e32 v3, v60, v4
	v_mul_f32_e32 v4, 0x3e000000, v13
	v_max_f32_e32 v4, 0, v4
	v_fmac_f32_e32 v3, v59, v4
	v_mul_f32_e32 v4, 0x3e000000, v14
	v_max_f32_e32 v4, 0, v4
	v_fmac_f32_e32 v3, v57, v4
	v_mul_f32_e32 v4, 0x3e000000, v15
	v_max_f32_e32 v4, 0, v4
	v_fmac_f32_e32 v3, v56, v4
	v_mul_f32_e32 v4, 0x3e000000, v16
	v_max_f32_e32 v4, 0, v4
	v_fmac_f32_e32 v3, v55, v4
	v_mul_f32_e32 v4, 0x3e000000, v17
	v_max_f32_e32 v4, 0, v4
	v_fmac_f32_e32 v3, v54, v4
	ds_write_b32 v63, v2
	ds_write_b32 v63, v3 offset:32800
	v_cvt_pk_bf16_f32 v2, v106, v107
	v_cvt_pk_bf16_f32 v3, v108, v109
	v_cvt_pk_bf16_f32 v4, v110, v111
	v_cvt_pk_bf16_f32 v5, v112, v113
	v_add_co_u32_e32 v8, vcc, s3, v40
	v_lshlrev_b32_e32 v6, 16, v2
	v_sub_f32_e32 v6, v106, v6
	v_and_b32_e32 v7, 0xffff0000, v2
	v_sub_f32_e32 v7, v107, v7
	v_cvt_pk_bf16_f32 v6, v6, v7
	v_and_b32_e32 v7, 0xffff0000, v3
	v_lshlrev_b32_e32 v6, 16, v3
	v_sub_f32_e32 v6, v108, v6
	v_sub_f32_e32 v7, v109, v7
	v_cvt_pk_bf16_f32 v6, v6, v7
	v_and_b32_e32 v7, 0xffff0000, v4
	v_lshlrev_b32_e32 v6, 16, v4
	v_sub_f32_e32 v6, v110, v6
	v_sub_f32_e32 v7, v111, v7
	v_cvt_pk_bf16_f32 v6, v6, v7
	v_and_b32_e32 v7, 0xffff0000, v5
	v_lshlrev_b32_e32 v6, 16, v5
	v_sub_f32_e32 v6, v112, v6
	v_sub_f32_e32 v7, v113, v7
	v_cvt_pk_bf16_f32 v6, v6, v7
	v_cvt_pk_bf16_f32 v34, v92, v93
	v_cvt_pk_bf16_f32 v35, v94, v95
	v_cvt_pk_bf16_f32 v36, v102, v103
	v_cvt_pk_bf16_f32 v37, v104, v105
	v_addc_co_u32_e32 v9, vcc, 0, v41, vcc
	v_lshlrev_b32_e32 v6, 16, v34
	v_sub_f32_e32 v6, v92, v6
	v_and_b32_e32 v7, 0xffff0000, v34
	v_sub_f32_e32 v7, v93, v7
	v_cvt_pk_bf16_f32 v6, v6, v7
	v_and_b32_e32 v7, 0xffff0000, v35
	v_lshlrev_b32_e32 v6, 16, v35
	v_sub_f32_e32 v6, v94, v6
	v_sub_f32_e32 v7, v95, v7
	v_cvt_pk_bf16_f32 v6, v6, v7
	v_and_b32_e32 v7, 0xffff0000, v36
	v_lshlrev_b32_e32 v6, 16, v36
	v_sub_f32_e32 v6, v102, v6
	v_sub_f32_e32 v7, v103, v7
	v_cvt_pk_bf16_f32 v6, v6, v7
	v_and_b32_e32 v7, 0xffff0000, v37
	v_lshlrev_b32_e32 v6, 16, v37
	v_sub_f32_e32 v6, v104, v6
	v_sub_f32_e32 v7, v105, v7
	v_cvt_pk_bf16_f32 v6, v6, v7
	v_cvt_pk_bf16_f32 v76, v72, v73
	v_cvt_pk_bf16_f32 v77, v74, v75
	v_cvt_pk_bf16_f32 v78, v88, v89
	v_cvt_pk_bf16_f32 v79, v90, v91
	s_movk_i32 s3, 0x6000
	v_lshlrev_b32_e32 v6, 16, v76
	v_sub_f32_e32 v6, v72, v6
	v_and_b32_e32 v7, 0xffff0000, v76
	v_sub_f32_e32 v7, v73, v7
	v_cvt_pk_bf16_f32 v6, v6, v7
	v_and_b32_e32 v7, 0xffff0000, v77
	v_lshlrev_b32_e32 v6, 16, v77
	v_sub_f32_e32 v6, v74, v6
	v_sub_f32_e32 v7, v75, v7
	v_cvt_pk_bf16_f32 v6, v6, v7
	v_and_b32_e32 v7, 0xffff0000, v78
	v_lshlrev_b32_e32 v6, 16, v78
	v_sub_f32_e32 v6, v88, v6
	v_sub_f32_e32 v7, v89, v7
	v_cvt_pk_bf16_f32 v6, v6, v7
	v_and_b32_e32 v7, 0xffff0000, v79
	v_lshlrev_b32_e32 v6, 16, v79
	v_sub_f32_e32 v6, v90, v6
	v_sub_f32_e32 v7, v91, v7
	v_cvt_pk_bf16_f32 v6, v6, v7
	v_cvt_pk_bf16_f32 v72, v64, v65
	v_cvt_pk_bf16_f32 v73, v66, v67
	v_cvt_pk_bf16_f32 v74, v68, v69
	v_cvt_pk_bf16_f32 v75, v70, v71
	s_nop 0
	v_lshlrev_b32_e32 v6, 16, v72
	v_sub_f32_e32 v6, v64, v6
	v_and_b32_e32 v7, 0xffff0000, v72
	v_sub_f32_e32 v7, v65, v7
	v_cvt_pk_bf16_f32 v6, v6, v7
	v_and_b32_e32 v7, 0xffff0000, v73
	v_lshlrev_b32_e32 v6, 16, v73
	v_sub_f32_e32 v6, v66, v6
	v_sub_f32_e32 v7, v67, v7
	v_cvt_pk_bf16_f32 v6, v6, v7
	v_and_b32_e32 v7, 0xffff0000, v74
	v_lshlrev_b32_e32 v6, 16, v74
	v_sub_f32_e32 v6, v68, v6
	v_sub_f32_e32 v7, v69, v7
	v_cvt_pk_bf16_f32 v6, v6, v7
	v_and_b32_e32 v7, 0xffff0000, v75
	v_lshlrev_b32_e32 v6, 16, v75
	v_sub_f32_e32 v6, v70, v6
	v_sub_f32_e32 v7, v71, v7
	v_cvt_pk_bf16_f32 v6, v6, v7
	s_nop 0
	v_lshl_add_u64 v[6:7], v[40:41], 0, s[8:9]
	s_mov_b64 s[8:9], 0x4080
	s_cbranch_scc1 .Lsbr_w0_2
	s_waitcnt vmcnt(24)
	s_branch .Lsbr_c_2

; __device__ __forceinline__ void idx_tile(const IdxQ& q, const IdxKey& k, float (&s)[2]) {
;     f32x16 acc;
; #pragma unroll
;     for (int i = 0; i < 16; ++i) acc[i] = 0.f;
; #pragma unroll
;     for (int ks = 0; ks < 4; ++ks) {
;         acc = __builtin_amdgcn_mfma_f32_32x32x16_bf16(q.hi[ks], k.hi[ks], acc, 0, 0, 0);
;         if (IDX_SPLIT == 3) { acc = __builtin_amdgcn_mfma_f32_32x32x16_bf16(q.hi[ks], k.lo[ks], acc, 0, 0, 0); acc = __builtin_amdgcn_mfma_f32_32x32x16_bf16(q.lo[ks], k.hi[ks], acc, 0, 0, 0); }
;     }
; #pragma unroll
;     for (int e = 0; e < 2; ++e) {
;         float t = 0.f;
; #pragma unroll
;         for (int i = 0; i < 8; ++i) t += fmaxf(acc[e * 8 + i] * IDX_SCALE, 0.f) * q.w[e * 8 + i];
;         s[e] = t;
;     }
; __device__ __forceinline__ void idx_sample_batch_unit(const Params& p, PG8_LAS unsigned char* lds, int bs) {
;     ...
;         for (int tt = 0; tt < 4; ++tt) {
;             idx_cvt_key(raw, k);
;             if (tt < 3) idx_load_raw(raw, pbase + (size_t)(tt + 1) * 32 * IDD);
;             float s2[2]; idx_tile(q, k, s2);
;             const int col = pg * PAGE + tt * 32 + r;
;             sc[(2 * kh) * SCS_LDL + col] = s2[0]; sc[(2 * kh + 1) * SCS_LDL + col] = s2[1];
.Lsbr_c_2:
	v_mov_b64_e32 v[102:103], v[190:191]
	v_mov_b64_e32 v[104:105], v[192:193]
	v_mov_b64_e32 v[106:107], v[194:195]
	v_mov_b64_e32 v[108:109], v[196:197]
	v_mov_b64_e32 v[88:89], v[198:199]
	v_mov_b64_e32 v[90:91], v[200:201]
	v_mov_b64_e32 v[92:93], v[202:203]
	v_mov_b64_e32 v[94:95], v[204:205]
	v_mov_b64_e32 v[80:81], v[206:207]
	v_mov_b64_e32 v[82:83], v[208:209]
	v_mov_b64_e32 v[84:85], v[210:211]
	v_mov_b64_e32 v[86:87], v[212:213]
	v_mov_b64_e32 v[64:65], v[214:215]
	v_mov_b64_e32 v[66:67], v[216:217]
	v_mov_b64_e32 v[68:69], v[218:219]
	v_mov_b64_e32 v[70:71], v[220:221]
	s_cbranch_scc1 .Lsbr_n_2
	v_add_u32_e32 v118, 0x4000, v116
	global_load_dwordx4 v[190:193], v118, s[44:45]
	global_load_dwordx4 v[194:197], v118, s[44:45] offset:16
	global_load_dwordx4 v[198:201], v118, s[44:45] offset:64
	global_load_dwordx4 v[202:205], v118, s[44:45] offset:80
	global_load_dwordx4 v[206:209], v118, s[44:45] offset:128
	global_load_dwordx4 v[210:213], v118, s[44:45] offset:144
	global_load_dwordx4 v[214:217], v118, s[44:45] offset:192
	global_load_dwordx4 v[218:221], v118, s[44:45] offset:208
.Lsbr_n_2:
	v_lshl_add_u64 v[6:7], v[40:41], 0, s[8:9]
	s_mov_b64 s[8:9], 0x4040
	v_lshl_add_u64 v[6:7], v[40:41], 0, s[8:9]
	s_mov_b64 s[8:9], 0x4000
	v_lshl_add_u64 v[6:7], v[40:41], 0, s[8:9]
	v_mfma_f32_32x32x16_bf16 v[2:17], v[30:33], v[2:5], 0
	s_mov_b64 s[8:9], 0x60c0
	v_mfma_f32_32x32x16_bf16 v[2:17], v[26:29], v[34:37], v[2:17]
	v_mfma_f32_32x32x16_bf16 v[2:17], v[22:25], v[76:79], v[2:17]
	v_mfma_f32_32x32x16_bf16 v[2:17], v[18:21], v[72:75], v[2:17]
	s_nop 11
	v_mul_f32_e32 v2, 0x3e000000, v2
	v_max_f32_e32 v2, 0, v2
	v_mul_f32_e32 v3, 0x3e000000, v3
	v_fma_f32 v2, v52, v2, 0
	v_max_f32_e32 v3, 0, v3
	v_fmac_f32_e32 v2, v51, v3
	v_mul_f32_e32 v3, 0x3e000000, v4
	v_max_f32_e32 v3, 0, v3
	v_fmac_f32_e32 v2, v50, v3
	v_mul_f32_e32 v3, 0x3e000000, v5
	v_max_f32_e32 v3, 0, v3
	v_fmac_f32_e32 v2, v49, v3
	v_mul_f32_e32 v3, 0x3e000000, v6
	v_max_f32_e32 v3, 0, v3
	v_fmac_f32_e32 v2, v48, v3
	v_mul_f32_e32 v3, 0x3e000000, v7
	v_max_f32_e32 v3, 0, v3
	v_fmac_f32_e32 v2, v47, v3
	v_mul_f32_e32 v3, 0x3e000000, v8
	v_max_f32_e32 v3, 0, v3
	v_fmac_f32_e32 v2, v46, v3
	v_mul_f32_e32 v3, 0x3e000000, v9
	v_max_f32_e32 v3, 0, v3
	v_fmac_f32_e32 v2, v45, v3
	v_mul_f32_e32 v3, 0x3e000000, v10
	v_max_f32_e32 v3, 0, v3
	v_mul_f32_e32 v4, 0x3e000000, v11
	v_fma_f32 v3, v62, v3, 0
	v_max_f32_e32 v4, 0, v4
	v_fmac_f32_e32 v3, v61, v4
	v_mul_f32_e32 v4, 0x3e000000, v12
	v_max_f32_e32 v4, 0, v4
	v_fmac_f32_e32 v3, v60, v4
	v_mul_f32_e32 v4, 0x3e000000, v13
	v_max_f32_e32 v4, 0, v4
	v_fmac_f32_e32 v3, v59, v4
	v_mul_f32_e32 v4, 0x3e000000, v14
	v_max_f32_e32 v4, 0, v4
	v_fmac_f32_e32 v3, v57, v4
	v_mul_f32_e32 v4, 0x3e000000, v15
	v_max_f32_e32 v4, 0, v4
	v_fmac_f32_e32 v3, v56, v4
	v_mul_f32_e32 v4, 0x3e000000, v16
	v_max_f32_e32 v4, 0, v4
	v_fmac_f32_e32 v3, v55, v4
	v_mul_f32_e32 v4, 0x3e000000, v17
	v_max_f32_e32 v4, 0, v4
	v_fmac_f32_e32 v3, v54, v4
	ds_write_b32 v63, v2 offset:128
	ds_write_b32 v63, v3 offset:32928
	v_cvt_pk_bf16_f32 v2, v102, v103
	v_cvt_pk_bf16_f32 v3, v104, v105
	v_cvt_pk_bf16_f32 v4, v106, v107
	v_cvt_pk_bf16_f32 v5, v108, v109
	v_add_co_u32_e32 v8, vcc, s3, v40
	v_lshlrev_b32_e32 v6, 16, v2
	v_sub_f32_e32 v6, v102, v6
	v_and_b32_e32 v7, 0xffff0000, v2
	v_sub_f32_e32 v7, v103, v7
	v_cvt_pk_bf16_f32 v6, v6, v7
	v_and_b32_e32 v7, 0xffff0000, v3
	v_lshlrev_b32_e32 v6, 16, v3
	v_sub_f32_e32 v6, v104, v6
	v_sub_f32_e32 v7, v105, v7
	v_cvt_pk_bf16_f32 v6, v6, v7
	v_and_b32_e32 v7, 0xffff0000, v4
	v_lshlrev_b32_e32 v6, 16, v4
	v_sub_f32_e32 v6, v106, v6
	v_sub_f32_e32 v7, v107, v7
	v_cvt_pk_bf16_f32 v6, v6, v7
	v_and_b32_e32 v7, 0xffff0000, v5
	v_lshlrev_b32_e32 v6, 16, v5
	v_sub_f32_e32 v6, v108, v6
	v_sub_f32_e32 v7, v109, v7
	v_cvt_pk_bf16_f32 v6, v6, v7
	v_cvt_pk_bf16_f32 v34, v88, v89
	v_cvt_pk_bf16_f32 v35, v90, v91
	v_cvt_pk_bf16_f32 v36, v92, v93
	v_cvt_pk_bf16_f32 v37, v94, v95
	v_addc_co_u32_e32 v9, vcc, 0, v41, vcc
	v_lshlrev_b32_e32 v6, 16, v34
	v_sub_f32_e32 v6, v88, v6
	v_and_b32_e32 v7, 0xffff0000, v34
	v_sub_f32_e32 v7, v89, v7
	v_cvt_pk_bf16_f32 v6, v6, v7
	v_and_b32_e32 v7, 0xffff0000, v35
	v_lshlrev_b32_e32 v6, 16, v35
	v_sub_f32_e32 v6, v90, v6
	v_sub_f32_e32 v7, v91, v7
	v_cvt_pk_bf16_f32 v6, v6, v7
	v_and_b32_e32 v7, 0xffff0000, v36
	v_lshlrev_b32_e32 v6, 16, v36
	v_sub_f32_e32 v6, v92, v6
	v_sub_f32_e32 v7, v93, v7
	v_cvt_pk_bf16_f32 v6, v6, v7
	v_and_b32_e32 v7, 0xffff0000, v37
	v_lshlrev_b32_e32 v6, 16, v37
	v_sub_f32_e32 v6, v94, v6
	v_sub_f32_e32 v7, v95, v7
	v_cvt_pk_bf16_f32 v6, v6, v7
	v_cvt_pk_bf16_f32 v72, v80, v81
	v_cvt_pk_bf16_f32 v73, v82, v83
	v_cvt_pk_bf16_f32 v74, v84, v85
	v_cvt_pk_bf16_f32 v75, v86, v87
	s_nop 0
	v_lshlrev_b32_e32 v6, 16, v72
	v_sub_f32_e32 v6, v80, v6
	v_and_b32_e32 v7, 0xffff0000, v72
	v_sub_f32_e32 v7, v81, v7
	v_cvt_pk_bf16_f32 v6, v6, v7
	v_and_b32_e32 v7, 0xffff0000, v73
	v_lshlrev_b32_e32 v6, 16, v73
	v_sub_f32_e32 v6, v82, v6
	v_sub_f32_e32 v7, v83, v7
	v_cvt_pk_bf16_f32 v6, v6, v7
	v_and_b32_e32 v7, 0xffff0000, v74
	v_lshlrev_b32_e32 v6, 16, v74
	v_sub_f32_e32 v6, v84, v6
	v_sub_f32_e32 v7, v85, v7
	v_cvt_pk_bf16_f32 v6, v6, v7
	v_and_b32_e32 v7, 0xffff0000, v75
	v_lshlrev_b32_e32 v6, 16, v75
	v_sub_f32_e32 v6, v86, v6
	v_sub_f32_e32 v7, v87, v7
	v_cvt_pk_bf16_f32 v6, v6, v7
	v_cvt_pk_bf16_f32 v76, v64, v65
	v_cvt_pk_bf16_f32 v77, v66, v67
	v_cvt_pk_bf16_f32 v78, v68, v69
	v_cvt_pk_bf16_f32 v79, v70, v71
	s_nop 0
	v_lshlrev_b32_e32 v6, 16, v76
	v_sub_f32_e32 v6, v64, v6
	v_and_b32_e32 v7, 0xffff0000, v76
	v_sub_f32_e32 v7, v65, v7
	v_cvt_pk_bf16_f32 v6, v6, v7
	v_and_b32_e32 v7, 0xffff0000, v77
	v_lshlrev_b32_e32 v6, 16, v77
	v_sub_f32_e32 v6, v66, v6
	v_sub_f32_e32 v7, v67, v7
	v_cvt_pk_bf16_f32 v6, v6, v7
	v_and_b32_e32 v7, 0xffff0000, v78
	v_lshlrev_b32_e32 v6, 16, v78
	v_sub_f32_e32 v6, v68, v6
	v_sub_f32_e32 v7, v69, v7
	v_cvt_pk_bf16_f32 v6, v6, v7
	v_and_b32_e32 v7, 0xffff0000, v79
	v_lshlrev_b32_e32 v6, 16, v79
	v_sub_f32_e32 v6, v70, v6
	v_sub_f32_e32 v7, v71, v7
	v_cvt_pk_bf16_f32 v6, v6, v7
	s_nop 0
	v_lshl_add_u64 v[6:7], v[40:41], 0, s[8:9]
	s_mov_b64 s[8:9], 0x6080
	s_cbranch_scc1 .Lsbr_w0_3
	s_waitcnt vmcnt(24)
	s_branch .Lsbr_c_3

; __device__ __forceinline__ void idx_load_raw(IdxRaw& raw, const float* kp) {
; #pragma unroll
;     for (int ks = 0; ks < 4; ++ks) { raw.v[2 * ks] = *(const f32x4*)(kp + ks * 16); raw.v[2 * ks + 1] = *(const f32x4*)(kp + ks * 16 + 4); }
; }
; __device__ __forceinline__ void idx_sample_batch_unit(const Params& p, PG8_LAS unsigned char* lds, int bs) {
;     ...
;             if (tt < 3) idx_load_raw(raw, pbase + (size_t)(tt + 1) * 32 * IDD);
.Lsbr_c_3:
	v_mov_b64_e32 v[102:103], v[222:223]
	v_mov_b64_e32 v[104:105], v[224:225]
	v_mov_b64_e32 v[106:107], v[226:227]
	v_mov_b64_e32 v[108:109], v[228:229]
	v_mov_b64_e32 v[88:89], v[230:231]
	v_mov_b64_e32 v[90:91], v[232:233]
	v_mov_b64_e32 v[92:93], v[234:235]
	v_mov_b64_e32 v[94:95], v[236:237]
	v_mov_b64_e32 v[80:81], v[240:241]
	v_mov_b64_e32 v[82:83], v[242:243]
	v_mov_b64_e32 v[84:85], v[244:245]
	v_mov_b64_e32 v[86:87], v[246:247]
	v_mov_b64_e32 v[64:65], v[248:249]
	v_mov_b64_e32 v[66:67], v[250:251]
	v_mov_b64_e32 v[68:69], v[252:253]
	v_mov_b64_e32 v[70:71], v[254:255]
	s_cbranch_scc1 .Lsbr_n_3
	v_add_u32_e32 v118, 0x6000, v116
	global_load_dwordx4 v[222:225], v118, s[44:45]
	global_load_dwordx4 v[226:229], v118, s[44:45] offset:16
	global_load_dwordx4 v[230:233], v118, s[44:45] offset:64
	global_load_dwordx4 v[234:237], v118, s[44:45] offset:80
	global_load_dwordx4 v[240:243], v118, s[44:45] offset:128
	global_load_dwordx4 v[244:247], v118, s[44:45] offset:144
	global_load_dwordx4 v[248:251], v118, s[44:45] offset:192
	global_load_dwordx4 v[252:255], v118, s[44:45] offset:208
; __device__ __forceinline__ void idx_tile(const IdxQ& q, const IdxKey& k, float (&s)[2]) {
;     f32x16 acc;
; #pragma unroll
;     for (int i = 0; i < 16; ++i) acc[i] = 0.f;
; #pragma unroll
;     for (int ks = 0; ks < 4; ++ks) {
;         acc = __builtin_amdgcn_mfma_f32_32x32x16_bf16(q.hi[ks], k.hi[ks], acc, 0, 0, 0);
;         if (IDX_SPLIT == 3) { acc = __builtin_amdgcn_mfma_f32_32x32x16_bf16(q.hi[ks], k.lo[ks], acc, 0, 0, 0); acc = __builtin_amdgcn_mfma_f32_32x32x16_bf16(q.lo[ks], k.hi[ks], acc, 0, 0, 0); }
;     }
; #pragma unroll
;     for (int e = 0; e < 2; ++e) {
;         float t = 0.f;
; #pragma unroll
;         for (int i = 0; i < 8; ++i) t += fmaxf(acc[e * 8 + i] * IDX_SCALE, 0.f) * q.w[e * 8 + i];
;         s[e] = t;
;     }
; __device__ __forceinline__ void idx_sample_batch_unit(const Params& p, PG8_LAS unsigned char* lds, int bs) {
;     ...
;         for (int tt = 0; tt < 4; ++tt) {
;             idx_cvt_key(raw, k);
;             if (tt < 3) idx_load_raw(raw, pbase + (size_t)(tt + 1) * 32 * IDD);
;             float s2[2]; idx_tile(q, k, s2);
;             const int col = pg * PAGE + tt * 32 + r;
;             sc[(2 * kh) * SCS_LDL + col] = s2[0]; sc[(2 * kh + 1) * SCS_LDL + col] = s2[1];
.Lsbr_n_3:
	v_lshl_add_u64 v[6:7], v[40:41], 0, s[8:9]
	s_mov_b64 s[8:9], 0x6040
	v_lshl_add_u64 v[6:7], v[40:41], 0, s[8:9]
	s_mov_b64 s[8:9], 0x6000
	v_lshl_add_u64 v[6:7], v[40:41], 0, s[8:9]
	v_mfma_f32_32x32x16_bf16 v[2:17], v[30:33], v[2:5], 0
	v_mfma_f32_32x32x16_bf16 v[2:17], v[26:29], v[34:37], v[2:17]
	v_mfma_f32_32x32x16_bf16 v[2:17], v[22:25], v[72:75], v[2:17]
	v_mfma_f32_32x32x16_bf16 v[2:17], v[18:21], v[76:79], v[2:17]
	s_nop 11
	v_mul_f32_e32 v2, 0x3e000000, v2
	v_max_f32_e32 v2, 0, v2
	v_mul_f32_e32 v3, 0x3e000000, v3
	v_fma_f32 v2, v52, v2, 0
	v_max_f32_e32 v3, 0, v3
	v_fmac_f32_e32 v2, v51, v3
	v_mul_f32_e32 v3, 0x3e000000, v4
	v_max_f32_e32 v3, 0, v3
	v_fmac_f32_e32 v2, v50, v3
	v_mul_f32_e32 v3, 0x3e000000, v5
	v_max_f32_e32 v3, 0, v3
	v_fmac_f32_e32 v2, v49, v3
	v_mul_f32_e32 v3, 0x3e000000, v6
	v_max_f32_e32 v3, 0, v3
	v_fmac_f32_e32 v2, v48, v3
	v_mul_f32_e32 v3, 0x3e000000, v7
	v_max_f32_e32 v3, 0, v3
	v_fmac_f32_e32 v2, v47, v3
	v_mul_f32_e32 v3, 0x3e000000, v8
	v_max_f32_e32 v3, 0, v3
	v_fmac_f32_e32 v2, v46, v3
	v_mul_f32_e32 v3, 0x3e000000, v9
	v_max_f32_e32 v3, 0, v3
	v_fmac_f32_e32 v2, v45, v3
	v_mul_f32_e32 v3, 0x3e000000, v10
	v_max_f32_e32 v3, 0, v3
	v_mul_f32_e32 v4, 0x3e000000, v11
	v_fma_f32 v3, v62, v3, 0
	v_max_f32_e32 v4, 0, v4
	v_fmac_f32_e32 v3, v61, v4
	v_mul_f32_e32 v4, 0x3e000000, v12
	v_max_f32_e32 v4, 0, v4
	v_fmac_f32_e32 v3, v60, v4
	v_mul_f32_e32 v4, 0x3e000000, v13
	v_max_f32_e32 v4, 0, v4
	v_fmac_f32_e32 v3, v59, v4
	v_mul_f32_e32 v4, 0x3e000000, v14
	v_max_f32_e32 v4, 0, v4
	v_fmac_f32_e32 v3, v57, v4
	v_mul_f32_e32 v4, 0x3e000000, v15
	v_max_f32_e32 v4, 0, v4
	v_fmac_f32_e32 v3, v56, v4
	v_mul_f32_e32 v4, 0x3e000000, v16
	v_max_f32_e32 v4, 0, v4
	v_fmac_f32_e32 v3, v55, v4
	v_mul_f32_e32 v4, 0x3e000000, v17
	v_max_f32_e32 v4, 0, v4
	v_fmac_f32_e32 v3, v54, v4
	ds_write_b32 v63, v2 offset:256
	ds_write_b32 v63, v3 offset:33056
	v_cvt_pk_bf16_f32 v2, v102, v103
	v_cvt_pk_bf16_f32 v3, v104, v105
	v_cvt_pk_bf16_f32 v4, v106, v107
	v_cvt_pk_bf16_f32 v5, v108, v109
	v_lshlrev_b32_e32 v6, 16, v2
	v_sub_f32_e32 v6, v102, v6
	v_and_b32_e32 v7, 0xffff0000, v2
	v_sub_f32_e32 v7, v103, v7
	v_cvt_pk_bf16_f32 v6, v6, v7
	v_and_b32_e32 v7, 0xffff0000, v3
	v_lshlrev_b32_e32 v6, 16, v3
	v_sub_f32_e32 v6, v104, v6
	v_sub_f32_e32 v7, v105, v7
	v_cvt_pk_bf16_f32 v6, v6, v7
	v_and_b32_e32 v7, 0xffff0000, v4
	v_lshlrev_b32_e32 v6, 16, v4
	v_sub_f32_e32 v6, v106, v6
	v_sub_f32_e32 v7, v107, v7
	v_cvt_pk_bf16_f32 v6, v6, v7
	v_and_b32_e32 v7, 0xffff0000, v5
	v_lshlrev_b32_e32 v6, 16, v5
	v_sub_f32_e32 v6, v108, v6
	v_sub_f32_e32 v7, v109, v7
	v_cvt_pk_bf16_f32 v6, v6, v7
	v_cvt_pk_bf16_f32 v34, v88, v89
	v_cvt_pk_bf16_f32 v35, v90, v91
	v_cvt_pk_bf16_f32 v36, v92, v93
	v_cvt_pk_bf16_f32 v37, v94, v95
	s_nop 0
	v_lshlrev_b32_e32 v6, 16, v34
	v_sub_f32_e32 v6, v88, v6
	v_and_b32_e32 v7, 0xffff0000, v34
	v_sub_f32_e32 v7, v89, v7
	v_cvt_pk_bf16_f32 v6, v6, v7
	v_and_b32_e32 v7, 0xffff0000, v35
	v_lshlrev_b32_e32 v6, 16, v35
	v_sub_f32_e32 v6, v90, v6
	v_sub_f32_e32 v7, v91, v7
	v_cvt_pk_bf16_f32 v6, v6, v7
	v_and_b32_e32 v7, 0xffff0000, v36
	v_lshlrev_b32_e32 v6, 16, v36
	v_sub_f32_e32 v6, v92, v6
	v_sub_f32_e32 v7, v93, v7
	v_cvt_pk_bf16_f32 v6, v6, v7
	v_and_b32_e32 v7, 0xffff0000, v37
	v_lshlrev_b32_e32 v6, 16, v37
	v_sub_f32_e32 v6, v94, v6
	v_sub_f32_e32 v7, v95, v7
	v_cvt_pk_bf16_f32 v6, v6, v7
	v_cvt_pk_bf16_f32 v72, v80, v81
	v_cvt_pk_bf16_f32 v73, v82, v83
	v_cvt_pk_bf16_f32 v74, v84, v85
	v_cvt_pk_bf16_f32 v75, v86, v87
	s_nop 0
	v_lshlrev_b32_e32 v6, 16, v72
	v_sub_f32_e32 v6, v80, v6
	v_and_b32_e32 v7, 0xffff0000, v72
	v_sub_f32_e32 v7, v81, v7
	v_cvt_pk_bf16_f32 v6, v6, v7
	v_and_b32_e32 v7, 0xffff0000, v73
	v_lshlrev_b32_e32 v6, 16, v73
	v_sub_f32_e32 v6, v82, v6
	v_sub_f32_e32 v7, v83, v7
	v_cvt_pk_bf16_f32 v6, v6, v7
	v_and_b32_e32 v7, 0xffff0000, v74
	v_lshlrev_b32_e32 v6, 16, v74
	v_sub_f32_e32 v6, v84, v6
	v_sub_f32_e32 v7, v85, v7
	v_cvt_pk_bf16_f32 v6, v6, v7
	v_and_b32_e32 v7, 0xffff0000, v75
	v_lshlrev_b32_e32 v6, 16, v75
	v_sub_f32_e32 v6, v86, v6
	v_sub_f32_e32 v7, v87, v7
	v_cvt_pk_bf16_f32 v6, v6, v7
	v_cvt_pk_bf16_f32 v76, v64, v65
	v_cvt_pk_bf16_f32 v77, v66, v67
	v_cvt_pk_bf16_f32 v78, v68, v69
	v_cvt_pk_bf16_f32 v79, v70, v71
	s_nop 0
	v_lshlrev_b32_e32 v6, 16, v76
	v_sub_f32_e32 v6, v64, v6
	v_and_b32_e32 v7, 0xffff0000, v76
	v_sub_f32_e32 v7, v65, v7
	v_cvt_pk_bf16_f32 v6, v6, v7
	v_and_b32_e32 v7, 0xffff0000, v77
	v_lshlrev_b32_e32 v6, 16, v77
	v_sub_f32_e32 v6, v66, v6
	v_sub_f32_e32 v7, v67, v7
	v_cvt_pk_bf16_f32 v6, v6, v7
	v_and_b32_e32 v7, 0xffff0000, v78
	v_lshlrev_b32_e32 v6, 16, v78
	v_sub_f32_e32 v6, v68, v6
	v_sub_f32_e32 v7, v69, v7
	v_cvt_pk_bf16_f32 v6, v6, v7
	v_and_b32_e32 v7, 0xffff0000, v79
	v_lshlrev_b32_e32 v6, 16, v79
	v_sub_f32_e32 v6, v70, v6
	v_sub_f32_e32 v7, v71, v7
	v_cvt_pk_bf16_f32 v6, v6, v7
	s_nop 0
	v_mfma_f32_32x32x16_bf16 v[2:17], v[30:33], v[2:5], 0
	v_mfma_f32_32x32x16_bf16 v[2:17], v[26:29], v[34:37], v[2:17]
	v_mfma_f32_32x32x16_bf16 v[2:17], v[22:25], v[72:75], v[2:17]
	v_mfma_f32_32x32x16_bf16 v[2:17], v[18:21], v[76:79], v[2:17]
	s_nop 11
	v_mul_f32_e32 v2, 0x3e000000, v2
	v_max_f32_e32 v2, 0, v2
	v_mul_f32_e32 v3, 0x3e000000, v3
	v_fma_f32 v2, v52, v2, 0
	v_max_f32_e32 v3, 0, v3
	v_fmac_f32_e32 v2, v51, v3
	v_mul_f32_e32 v3, 0x3e000000, v4
	v_max_f32_e32 v3, 0, v3
	v_fmac_f32_e32 v2, v50, v3
	v_mul_f32_e32 v3, 0x3e000000, v5
	v_max_f32_e32 v3, 0, v3
	v_fmac_f32_e32 v2, v49, v3
	v_mul_f32_e32 v3, 0x3e000000, v6
	v_max_f32_e32 v3, 0, v3
	v_fmac_f32_e32 v2, v48, v3
	v_mul_f32_e32 v3, 0x3e000000, v7
	v_max_f32_e32 v3, 0, v3
	v_fmac_f32_e32 v2, v47, v3
	v_mul_f32_e32 v3, 0x3e000000, v8
	v_max_f32_e32 v3, 0, v3
	v_fmac_f32_e32 v2, v46, v3
	v_mul_f32_e32 v3, 0x3e000000, v9
	v_max_f32_e32 v3, 0, v3
	v_fmac_f32_e32 v2, v45, v3
	v_mul_f32_e32 v3, 0x3e000000, v10
	v_max_f32_e32 v3, 0, v3
	v_mul_f32_e32 v4, 0x3e000000, v11
	v_fma_f32 v3, v62, v3, 0
	v_max_f32_e32 v4, 0, v4
	v_fmac_f32_e32 v3, v61, v4
	v_mul_f32_e32 v4, 0x3e000000, v12
	v_max_f32_e32 v4, 0, v4
	v_fmac_f32_e32 v3, v60, v4
	v_mul_f32_e32 v4, 0x3e000000, v13
	v_max_f32_e32 v4, 0, v4
	v_fmac_f32_e32 v3, v59, v4
	v_mul_f32_e32 v4, 0x3e000000, v14
	v_max_f32_e32 v4, 0, v4
	v_fmac_f32_e32 v3, v57, v4
	v_mul_f32_e32 v4, 0x3e000000, v15
	v_max_f32_e32 v4, 0, v4
	v_fmac_f32_e32 v3, v56, v4
	v_mul_f32_e32 v4, 0x3e000000, v16
	v_max_f32_e32 v4, 0, v4
	v_fmac_f32_e32 v3, v55, v4
	v_mul_f32_e32 v4, 0x3e000000, v17
	v_max_f32_e32 v4, 0, v4
	v_fmac_f32_e32 v3, v54, v4
	ds_write_b32 v63, v2 offset:384
	ds_write_b32 v63, v3 offset:33184
	v_add_u32_e32 v63, 0x1000, v63
	s_cbranch_scc0 .LBB0_1694
